# variant: waves 4-7 keep s_setprio 1 after the K-loops (through epilogues and later phases) instead of dropping back to 0 per unit
# baseline (speedup 1.0000x reference)
.LBB0_1790:
	ds_read_b128 v[146:149], v159
	ds_read_b128 v[150:153], v159 offset:1024
	ds_read_b128 v[164:167], v159 offset:2048
	ds_read_b128 v[168:171], v159 offset:3072
	ds_read_b128 v[172:175], v160
	ds_read_b128 v[176:179], v160 offset:1024
	ds_read_b128 v[186:189], v160 offset:2048
	ds_read_b128 v[190:193], v160 offset:3072
	s_add_u32 s79, s6, 0xfff00080
	s_addc_u32 s80, s7, -1
	s_cmp_eq_u32 s78, 60
	s_cselect_b32 s91, s45, s80
	s_cselect_b32 s90, s74, s79
	s_cselect_b32 s89, s43, s77
	s_cselect_b32 s88, s75, s76
	s_add_i32 m0, s33, 0xc000
	ds_read_b128 v[194:197], v161
	ds_read_b128 v[198:201], v161 offset:1024
	ds_read_b128 v[202:205], v161 offset:2048
	ds_read_b128 v[206:209], v161 offset:3072
	ds_read_b128 v[210:213], v161 offset:4096
	ds_read_b128 v[214:217], v161 offset:5120
	ds_read_b128 v[218:221], v161 offset:6144
	ds_read_b128 v[222:225], v161 offset:7168
	global_load_lds_dwordx4 v138, s[6:7]
	s_add_i32 m0, s33, 0xe000
	s_nop 0
	global_load_lds_dwordx4 v140, s[6:7]
	s_waitcnt vmcnt(8)
	s_waitcnt lgkmcnt(0)
	s_barrier
	v_mfma_f32_16x16x32_bf16 v[126:129], v[146:149], v[194:197], v[126:129]
	v_mfma_f32_16x16x32_bf16 v[126:129], v[150:153], v[198:201], v[126:129]
	v_mfma_f32_16x16x32_bf16 v[122:125], v[164:167], v[194:197], v[122:125]
	v_mfma_f32_16x16x32_bf16 v[122:125], v[168:171], v[198:201], v[122:125]
	v_mfma_f32_16x16x32_bf16 v[118:121], v[172:175], v[194:197], v[118:121]
	v_mfma_f32_16x16x32_bf16 v[118:121], v[176:179], v[198:201], v[118:121]
	v_mfma_f32_16x16x32_bf16 v[110:113], v[186:189], v[194:197], v[110:113]
	v_mfma_f32_16x16x32_bf16 v[110:113], v[190:193], v[198:201], v[110:113]
	v_mfma_f32_16x16x32_bf16 v[114:117], v[146:149], v[202:205], v[114:117]
	v_mfma_f32_16x16x32_bf16 v[114:117], v[150:153], v[206:209], v[114:117]
	v_mfma_f32_16x16x32_bf16 v[106:109], v[164:167], v[202:205], v[106:109]
	v_mfma_f32_16x16x32_bf16 v[106:109], v[168:171], v[206:209], v[106:109]
	v_mfma_f32_16x16x32_bf16 v[102:105], v[172:175], v[202:205], v[102:105]
	v_mfma_f32_16x16x32_bf16 v[102:105], v[176:179], v[206:209], v[102:105]
	v_mfma_f32_16x16x32_bf16 v[94:97], v[186:189], v[202:205], v[94:97]
	v_mfma_f32_16x16x32_bf16 v[94:97], v[190:193], v[206:209], v[94:97]
	v_mfma_f32_16x16x32_bf16 v[98:101], v[146:149], v[210:213], v[98:101]
	v_mfma_f32_16x16x32_bf16 v[98:101], v[150:153], v[214:217], v[98:101]
	v_mfma_f32_16x16x32_bf16 v[90:93], v[164:167], v[210:213], v[90:93]
	v_mfma_f32_16x16x32_bf16 v[90:93], v[168:171], v[214:217], v[90:93]
	v_mfma_f32_16x16x32_bf16 v[86:89], v[172:175], v[210:213], v[86:89]
	v_mfma_f32_16x16x32_bf16 v[86:89], v[176:179], v[214:217], v[86:89]
	v_mfma_f32_16x16x32_bf16 v[78:81], v[186:189], v[210:213], v[78:81]
	v_mfma_f32_16x16x32_bf16 v[78:81], v[190:193], v[214:217], v[78:81]
	v_mfma_f32_16x16x32_bf16 v[82:85], v[146:149], v[218:221], v[82:85]
	v_mfma_f32_16x16x32_bf16 v[82:85], v[150:153], v[222:225], v[82:85]
	v_mfma_f32_16x16x32_bf16 v[74:77], v[164:167], v[218:221], v[74:77]
	v_mfma_f32_16x16x32_bf16 v[74:77], v[168:171], v[222:225], v[74:77]
	v_mfma_f32_16x16x32_bf16 v[70:73], v[172:175], v[218:221], v[70:73]
	v_mfma_f32_16x16x32_bf16 v[70:73], v[176:179], v[222:225], v[70:73]
	v_mfma_f32_16x16x32_bf16 v[66:69], v[186:189], v[218:221], v[66:69]
	v_mfma_f32_16x16x32_bf16 v[66:69], v[190:193], v[222:225], v[66:69]
	s_barrier
	s_add_i32 s79, s69, s25
	s_add_u32 s98, s88, 0x80
	s_addc_u32 s99, s89, 0
	s_mov_b32 m0, s79
	ds_read_b128 v[194:197], v161 offset:16384
	ds_read_b128 v[198:201], v161 offset:17408
	ds_read_b128 v[202:205], v161 offset:18432
	ds_read_b128 v[206:209], v161 offset:19456
	ds_read_b128 v[210:213], v161 offset:20480
	ds_read_b128 v[214:217], v161 offset:21504
	ds_read_b128 v[218:221], v161 offset:22528
	ds_read_b128 v[222:225], v161 offset:23552
	global_load_lds_dwordx4 v132, s[88:89]
	s_add_i32 m0, s79, 0x2000
	s_add_u32 s80, s88, 0x100000
	s_addc_u32 s81, s89, 0
	s_add_i32 s79, s70, s25
	global_load_lds_dwordx4 v136, s[88:89]
	s_mov_b32 m0, s79
	global_load_lds_dwordx4 v132, s[80:81]
	s_add_i32 m0, s79, 0x2000
	s_nop 0
	global_load_lds_dwordx4 v136, s[80:81]
	s_add_u32 s100, s90, 0x80
	s_addc_u32 s101, s91, 0
	s_mov_b32 m0, s33
	s_nop 0
	global_load_lds_dwordx4 v130, s[90:91]
	s_mov_b32 m0, s35
	s_nop 0
	global_load_lds_dwordx4 v134, s[90:91]
	s_waitcnt vmcnt(8)
	s_waitcnt lgkmcnt(0)
	s_barrier
	v_mfma_f32_16x16x32_bf16 v[62:65], v[146:149], v[194:197], v[62:65]
	v_mfma_f32_16x16x32_bf16 v[62:65], v[150:153], v[198:201], v[62:65]
	v_mfma_f32_16x16x32_bf16 v[58:61], v[164:167], v[194:197], v[58:61]
	v_mfma_f32_16x16x32_bf16 v[58:61], v[168:171], v[198:201], v[58:61]
	v_mfma_f32_16x16x32_bf16 v[54:57], v[172:175], v[194:197], v[54:57]
	v_mfma_f32_16x16x32_bf16 v[54:57], v[176:179], v[198:201], v[54:57]
	v_mfma_f32_16x16x32_bf16 v[46:49], v[186:189], v[194:197], v[46:49]
	v_mfma_f32_16x16x32_bf16 v[46:49], v[190:193], v[198:201], v[46:49]
	v_mfma_f32_16x16x32_bf16 v[50:53], v[146:149], v[202:205], v[50:53]
	v_mfma_f32_16x16x32_bf16 v[50:53], v[150:153], v[206:209], v[50:53]
	v_mfma_f32_16x16x32_bf16 v[42:45], v[164:167], v[202:205], v[42:45]
	v_mfma_f32_16x16x32_bf16 v[42:45], v[168:171], v[206:209], v[42:45]
	v_mfma_f32_16x16x32_bf16 v[38:41], v[172:175], v[202:205], v[38:41]
	v_mfma_f32_16x16x32_bf16 v[38:41], v[176:179], v[206:209], v[38:41]
	v_mfma_f32_16x16x32_bf16 v[30:33], v[186:189], v[202:205], v[30:33]
	v_mfma_f32_16x16x32_bf16 v[30:33], v[190:193], v[206:209], v[30:33]
	v_mfma_f32_16x16x32_bf16 v[34:37], v[146:149], v[210:213], v[34:37]
	v_mfma_f32_16x16x32_bf16 v[34:37], v[150:153], v[214:217], v[34:37]
	v_mfma_f32_16x16x32_bf16 v[26:29], v[164:167], v[210:213], v[26:29]
	v_mfma_f32_16x16x32_bf16 v[26:29], v[168:171], v[214:217], v[26:29]
	v_mfma_f32_16x16x32_bf16 v[22:25], v[172:175], v[210:213], v[22:25]
	v_mfma_f32_16x16x32_bf16 v[22:25], v[176:179], v[214:217], v[22:25]
	v_mfma_f32_16x16x32_bf16 v[14:17], v[186:189], v[210:213], v[14:17]
	v_mfma_f32_16x16x32_bf16 v[14:17], v[190:193], v[214:217], v[14:17]
	v_mfma_f32_16x16x32_bf16 v[18:21], v[146:149], v[218:221], v[18:21]
	v_mfma_f32_16x16x32_bf16 v[18:21], v[150:153], v[222:225], v[18:21]
	v_mfma_f32_16x16x32_bf16 v[10:13], v[164:167], v[218:221], v[10:13]
	v_mfma_f32_16x16x32_bf16 v[10:13], v[168:171], v[222:225], v[10:13]
	v_mfma_f32_16x16x32_bf16 v[6:9], v[172:175], v[218:221], v[6:9]
	v_mfma_f32_16x16x32_bf16 v[6:9], v[176:179], v[222:225], v[6:9]
	v_mfma_f32_16x16x32_bf16 v[2:5], v[186:189], v[218:221], v[2:5]
	v_mfma_f32_16x16x32_bf16 v[2:5], v[190:193], v[222:225], v[2:5]
	s_barrier
	s_add_i32 s79, 0, 0x18000
	s_add_i32 s82, 0, 0x1c000
	ds_read_b128 v[146:149], v246
	ds_read_b128 v[150:153], v246 offset:1024
	ds_read_b128 v[164:167], v246 offset:2048
	ds_read_b128 v[168:171], v246 offset:3072
	ds_read_b128 v[172:175], v247
	ds_read_b128 v[176:179], v247 offset:1024
	ds_read_b128 v[186:189], v247 offset:2048
	ds_read_b128 v[190:193], v247 offset:3072
	s_add_u32 s80, s90, 0x100000
	s_addc_u32 s81, s91, 0
	s_mov_b32 m0, s59
	ds_read_b128 v[194:197], v161 offset:32768
	ds_read_b128 v[198:201], v161 offset:33792
	ds_read_b128 v[202:205], v161 offset:34816
	ds_read_b128 v[206:209], v161 offset:35840
	ds_read_b128 v[210:213], v161 offset:36864
	ds_read_b128 v[214:217], v161 offset:37888
	ds_read_b128 v[218:221], v161 offset:38912
	ds_read_b128 v[222:225], v161 offset:39936
	global_load_lds_dwordx4 v130, s[80:81]
	s_mov_b32 m0, s62
	s_nop 0
	global_load_lds_dwordx4 v134, s[80:81]
	s_waitcnt vmcnt(8)
	s_waitcnt lgkmcnt(0)
	s_barrier
	v_mfma_f32_16x16x32_bf16 v[126:129], v[146:149], v[194:197], v[126:129]
	v_mfma_f32_16x16x32_bf16 v[126:129], v[150:153], v[198:201], v[126:129]
	v_mfma_f32_16x16x32_bf16 v[122:125], v[164:167], v[194:197], v[122:125]
	v_mfma_f32_16x16x32_bf16 v[122:125], v[168:171], v[198:201], v[122:125]
	v_mfma_f32_16x16x32_bf16 v[118:121], v[172:175], v[194:197], v[118:121]
	v_mfma_f32_16x16x32_bf16 v[118:121], v[176:179], v[198:201], v[118:121]
	v_mfma_f32_16x16x32_bf16 v[110:113], v[186:189], v[194:197], v[110:113]
	v_mfma_f32_16x16x32_bf16 v[110:113], v[190:193], v[198:201], v[110:113]
	v_mfma_f32_16x16x32_bf16 v[114:117], v[146:149], v[202:205], v[114:117]
	v_mfma_f32_16x16x32_bf16 v[114:117], v[150:153], v[206:209], v[114:117]
	v_mfma_f32_16x16x32_bf16 v[106:109], v[164:167], v[202:205], v[106:109]
	v_mfma_f32_16x16x32_bf16 v[106:109], v[168:171], v[206:209], v[106:109]
	v_mfma_f32_16x16x32_bf16 v[102:105], v[172:175], v[202:205], v[102:105]
	v_mfma_f32_16x16x32_bf16 v[102:105], v[176:179], v[206:209], v[102:105]
	v_mfma_f32_16x16x32_bf16 v[94:97], v[186:189], v[202:205], v[94:97]
	v_mfma_f32_16x16x32_bf16 v[94:97], v[190:193], v[206:209], v[94:97]
	v_mfma_f32_16x16x32_bf16 v[98:101], v[146:149], v[210:213], v[98:101]
	v_mfma_f32_16x16x32_bf16 v[98:101], v[150:153], v[214:217], v[98:101]
	v_mfma_f32_16x16x32_bf16 v[90:93], v[164:167], v[210:213], v[90:93]
	v_mfma_f32_16x16x32_bf16 v[90:93], v[168:171], v[214:217], v[90:93]
	v_mfma_f32_16x16x32_bf16 v[86:89], v[172:175], v[210:213], v[86:89]
	v_mfma_f32_16x16x32_bf16 v[86:89], v[176:179], v[214:217], v[86:89]
	v_mfma_f32_16x16x32_bf16 v[78:81], v[186:189], v[210:213], v[78:81]
	v_mfma_f32_16x16x32_bf16 v[78:81], v[190:193], v[214:217], v[78:81]
	v_mfma_f32_16x16x32_bf16 v[82:85], v[146:149], v[218:221], v[82:85]
	v_mfma_f32_16x16x32_bf16 v[82:85], v[150:153], v[222:225], v[82:85]
	v_mfma_f32_16x16x32_bf16 v[74:77], v[164:167], v[218:221], v[74:77]
	v_mfma_f32_16x16x32_bf16 v[74:77], v[168:171], v[222:225], v[74:77]
	v_mfma_f32_16x16x32_bf16 v[70:73], v[172:175], v[218:221], v[70:73]
	v_mfma_f32_16x16x32_bf16 v[70:73], v[176:179], v[222:225], v[70:73]
	v_mfma_f32_16x16x32_bf16 v[66:69], v[186:189], v[218:221], v[66:69]
	v_mfma_f32_16x16x32_bf16 v[66:69], v[190:193], v[222:225], v[66:69]
	s_barrier
	s_add_i32 s79, s79, s25
	s_mov_b32 m0, s79
	ds_read_b128 v[194:197], v161 offset:49152
	ds_read_b128 v[198:201], v161 offset:50176
	ds_read_b128 v[202:205], v161 offset:51200
	ds_read_b128 v[206:209], v161 offset:52224
	ds_read_b128 v[210:213], v161 offset:53248
	ds_read_b128 v[214:217], v161 offset:54272
	ds_read_b128 v[218:221], v161 offset:55296
	ds_read_b128 v[222:225], v161 offset:56320
	global_load_lds_dwordx4 v132, s[98:99]
	s_add_i32 m0, s79, 0x2000
	s_add_u32 s80, s88, 0x100080
	s_addc_u32 s81, s89, 0
	s_add_i32 s79, s82, s25
	global_load_lds_dwordx4 v136, s[98:99]
	s_mov_b32 m0, s79
	s_nop 0
	global_load_lds_dwordx4 v132, s[80:81]
	s_add_i32 m0, s79, 0x2000
	s_nop 0
	global_load_lds_dwordx4 v136, s[80:81]
	s_mov_b32 m0, s66
	s_nop 0
	global_load_lds_dwordx4 v130, s[100:101]
	s_mov_b32 m0, s67
	s_nop 0
	global_load_lds_dwordx4 v134, s[100:101]
	s_waitcnt vmcnt(8)
	s_waitcnt lgkmcnt(0)
	s_barrier
	v_mfma_f32_16x16x32_bf16 v[62:65], v[146:149], v[194:197], v[62:65]
	v_mfma_f32_16x16x32_bf16 v[62:65], v[150:153], v[198:201], v[62:65]
	v_mfma_f32_16x16x32_bf16 v[58:61], v[164:167], v[194:197], v[58:61]
	v_mfma_f32_16x16x32_bf16 v[58:61], v[168:171], v[198:201], v[58:61]
	v_mfma_f32_16x16x32_bf16 v[54:57], v[172:175], v[194:197], v[54:57]
	v_mfma_f32_16x16x32_bf16 v[54:57], v[176:179], v[198:201], v[54:57]
	v_mfma_f32_16x16x32_bf16 v[46:49], v[186:189], v[194:197], v[46:49]
	v_mfma_f32_16x16x32_bf16 v[46:49], v[190:193], v[198:201], v[46:49]
	v_mfma_f32_16x16x32_bf16 v[50:53], v[146:149], v[202:205], v[50:53]
	v_mfma_f32_16x16x32_bf16 v[50:53], v[150:153], v[206:209], v[50:53]
	v_mfma_f32_16x16x32_bf16 v[42:45], v[164:167], v[202:205], v[42:45]
	v_mfma_f32_16x16x32_bf16 v[42:45], v[168:171], v[206:209], v[42:45]
	v_mfma_f32_16x16x32_bf16 v[38:41], v[172:175], v[202:205], v[38:41]
	v_mfma_f32_16x16x32_bf16 v[38:41], v[176:179], v[206:209], v[38:41]
	v_mfma_f32_16x16x32_bf16 v[30:33], v[186:189], v[202:205], v[30:33]
	v_mfma_f32_16x16x32_bf16 v[30:33], v[190:193], v[206:209], v[30:33]
	v_mfma_f32_16x16x32_bf16 v[34:37], v[146:149], v[210:213], v[34:37]
	v_mfma_f32_16x16x32_bf16 v[34:37], v[150:153], v[214:217], v[34:37]
	v_mfma_f32_16x16x32_bf16 v[26:29], v[164:167], v[210:213], v[26:29]
	v_mfma_f32_16x16x32_bf16 v[26:29], v[168:171], v[214:217], v[26:29]
	v_mfma_f32_16x16x32_bf16 v[22:25], v[172:175], v[210:213], v[22:25]
	v_mfma_f32_16x16x32_bf16 v[22:25], v[176:179], v[214:217], v[22:25]
	v_mfma_f32_16x16x32_bf16 v[14:17], v[186:189], v[210:213], v[14:17]
	v_mfma_f32_16x16x32_bf16 v[14:17], v[190:193], v[214:217], v[14:17]
	v_mfma_f32_16x16x32_bf16 v[18:21], v[146:149], v[218:221], v[18:21]
	v_mfma_f32_16x16x32_bf16 v[18:21], v[150:153], v[222:225], v[18:21]
	v_mfma_f32_16x16x32_bf16 v[10:13], v[164:167], v[218:221], v[10:13]
	v_mfma_f32_16x16x32_bf16 v[10:13], v[168:171], v[222:225], v[10:13]
	v_mfma_f32_16x16x32_bf16 v[6:9], v[172:175], v[218:221], v[6:9]
	v_mfma_f32_16x16x32_bf16 v[6:9], v[176:179], v[222:225], v[6:9]
	v_mfma_f32_16x16x32_bf16 v[2:5], v[186:189], v[218:221], v[2:5]
	v_mfma_f32_16x16x32_bf16 v[2:5], v[190:193], v[222:225], v[2:5]
	s_barrier
	s_add_i32 s78, s78, 2
	s_add_u32 s6, s6, 0x100
	s_addc_u32 s7, s7, 0
	s_add_u32 s76, s76, 0x100
	s_addc_u32 s77, s77, 0
	s_cmp_gt_u32 s78, 61
	s_cbranch_scc0 .LBB0_1790
	s_and_b64 vcc, exec, s[40:41]
	s_cbranch_vccz .LBB0_1793
	s_barrier

.LBB0_2109:
	ds_read_b128 v[130:133], v155
	ds_read_b128 v[134:137], v155 offset:1024
	ds_read_b128 v[138:141], v155 offset:2048
	ds_read_b128 v[142:145], v155 offset:3072
	ds_read_b128 v[166:169], v176
	ds_read_b128 v[170:173], v176 offset:1024
	ds_read_b128 v[186:189], v176 offset:2048
	ds_read_b128 v[190:193], v176 offset:3072
	s_add_u32 s74, s50, 0xfff00080
	s_addc_u32 s75, s51, -1
	s_cmp_eq_u32 s73, 60
	s_cselect_b32 s85, s26, s75
	s_cselect_b32 s84, s45, s74
	s_cselect_b32 s83, s43, s72
	s_cselect_b32 s82, s70, s71
	s_add_i32 m0, s23, 0xc000
	ds_read_b128 v[194:197], v177
	ds_read_b128 v[198:201], v177 offset:1024
	ds_read_b128 v[202:205], v177 offset:2048
	ds_read_b128 v[206:209], v177 offset:3072
	ds_read_b128 v[210:213], v177 offset:4096
	ds_read_b128 v[214:217], v177 offset:5120
	ds_read_b128 v[218:221], v177 offset:6144
	ds_read_b128 v[222:225], v177 offset:7168
	global_load_lds_dwordx4 v158, s[50:51]
	s_add_i32 m0, s23, 0xe000
	s_nop 0
	global_load_lds_dwordx4 v160, s[50:51]
	s_waitcnt vmcnt(8)
	s_waitcnt lgkmcnt(0)
	s_barrier
	v_mfma_f32_16x16x32_bf16 v[126:129], v[130:133], v[194:197], v[126:129]
	v_mfma_f32_16x16x32_bf16 v[126:129], v[134:137], v[198:201], v[126:129]
	v_mfma_f32_16x16x32_bf16 v[122:125], v[138:141], v[194:197], v[122:125]
	v_mfma_f32_16x16x32_bf16 v[122:125], v[142:145], v[198:201], v[122:125]
	v_mfma_f32_16x16x32_bf16 v[118:121], v[166:169], v[194:197], v[118:121]
	v_mfma_f32_16x16x32_bf16 v[118:121], v[170:173], v[198:201], v[118:121]
	v_mfma_f32_16x16x32_bf16 v[114:117], v[186:189], v[194:197], v[114:117]
	v_mfma_f32_16x16x32_bf16 v[114:117], v[190:193], v[198:201], v[114:117]
	v_mfma_f32_16x16x32_bf16 v[110:113], v[130:133], v[202:205], v[110:113]
	v_mfma_f32_16x16x32_bf16 v[110:113], v[134:137], v[206:209], v[110:113]
	v_mfma_f32_16x16x32_bf16 v[106:109], v[138:141], v[202:205], v[106:109]
	v_mfma_f32_16x16x32_bf16 v[106:109], v[142:145], v[206:209], v[106:109]
	v_mfma_f32_16x16x32_bf16 v[102:105], v[166:169], v[202:205], v[102:105]
	v_mfma_f32_16x16x32_bf16 v[102:105], v[170:173], v[206:209], v[102:105]
	v_mfma_f32_16x16x32_bf16 v[98:101], v[186:189], v[202:205], v[98:101]
	v_mfma_f32_16x16x32_bf16 v[98:101], v[190:193], v[206:209], v[98:101]
	v_mfma_f32_16x16x32_bf16 v[94:97], v[130:133], v[210:213], v[94:97]
	v_mfma_f32_16x16x32_bf16 v[94:97], v[134:137], v[214:217], v[94:97]
	v_mfma_f32_16x16x32_bf16 v[90:93], v[138:141], v[210:213], v[90:93]
	v_mfma_f32_16x16x32_bf16 v[90:93], v[142:145], v[214:217], v[90:93]
	v_mfma_f32_16x16x32_bf16 v[86:89], v[166:169], v[210:213], v[86:89]
	v_mfma_f32_16x16x32_bf16 v[86:89], v[170:173], v[214:217], v[86:89]
	v_mfma_f32_16x16x32_bf16 v[82:85], v[186:189], v[210:213], v[82:85]
	v_mfma_f32_16x16x32_bf16 v[82:85], v[190:193], v[214:217], v[82:85]
	v_mfma_f32_16x16x32_bf16 v[78:81], v[130:133], v[218:221], v[78:81]
	v_mfma_f32_16x16x32_bf16 v[78:81], v[134:137], v[222:225], v[78:81]
	v_mfma_f32_16x16x32_bf16 v[74:77], v[138:141], v[218:221], v[74:77]
	v_mfma_f32_16x16x32_bf16 v[74:77], v[142:145], v[222:225], v[74:77]
	v_mfma_f32_16x16x32_bf16 v[70:73], v[166:169], v[218:221], v[70:73]
	v_mfma_f32_16x16x32_bf16 v[70:73], v[170:173], v[222:225], v[70:73]
	v_mfma_f32_16x16x32_bf16 v[66:69], v[186:189], v[218:221], v[66:69]
	v_mfma_f32_16x16x32_bf16 v[66:69], v[190:193], v[222:225], v[66:69]
	s_barrier
	s_add_i32 s74, s67, s3
	s_add_u32 s98, s82, 0x80
	s_addc_u32 s99, s83, 0
	s_mov_b32 m0, s74
	ds_read_b128 v[194:197], v177 offset:16384
	ds_read_b128 v[198:201], v177 offset:17408
	ds_read_b128 v[202:205], v177 offset:18432
	ds_read_b128 v[206:209], v177 offset:19456
	ds_read_b128 v[210:213], v177 offset:20480
	ds_read_b128 v[214:217], v177 offset:21504
	ds_read_b128 v[218:221], v177 offset:22528
	ds_read_b128 v[222:225], v177 offset:23552
	global_load_lds_dwordx4 v148, s[82:83]
	s_add_i32 m0, s74, 0x2000
	s_add_u32 s74, s82, 0x100000
	s_addc_u32 s75, s83, 0
	s_add_i32 s76, s68, s3
	global_load_lds_dwordx4 v152, s[82:83]
	s_mov_b32 m0, s76
	global_load_lds_dwordx4 v148, s[74:75]
	s_add_i32 m0, s76, 0x2000
	s_nop 0
	global_load_lds_dwordx4 v152, s[74:75]
	s_add_u32 s100, s84, 0x80
	s_addc_u32 s101, s85, 0
	s_mov_b32 m0, s23
	s_nop 0
	global_load_lds_dwordx4 v146, s[84:85]
	s_mov_b32 m0, s25
	s_nop 0
	global_load_lds_dwordx4 v150, s[84:85]
	s_waitcnt vmcnt(8)
	s_waitcnt lgkmcnt(0)
	s_barrier
	v_mfma_f32_16x16x32_bf16 v[62:65], v[130:133], v[194:197], v[62:65]
	v_mfma_f32_16x16x32_bf16 v[62:65], v[134:137], v[198:201], v[62:65]
	v_mfma_f32_16x16x32_bf16 v[58:61], v[138:141], v[194:197], v[58:61]
	v_mfma_f32_16x16x32_bf16 v[58:61], v[142:145], v[198:201], v[58:61]
	v_mfma_f32_16x16x32_bf16 v[54:57], v[166:169], v[194:197], v[54:57]
	v_mfma_f32_16x16x32_bf16 v[54:57], v[170:173], v[198:201], v[54:57]
	v_mfma_f32_16x16x32_bf16 v[50:53], v[186:189], v[194:197], v[50:53]
	v_mfma_f32_16x16x32_bf16 v[50:53], v[190:193], v[198:201], v[50:53]
	v_mfma_f32_16x16x32_bf16 v[46:49], v[130:133], v[202:205], v[46:49]
	v_mfma_f32_16x16x32_bf16 v[46:49], v[134:137], v[206:209], v[46:49]
	v_mfma_f32_16x16x32_bf16 v[42:45], v[138:141], v[202:205], v[42:45]
	v_mfma_f32_16x16x32_bf16 v[42:45], v[142:145], v[206:209], v[42:45]
	v_mfma_f32_16x16x32_bf16 v[38:41], v[166:169], v[202:205], v[38:41]
	v_mfma_f32_16x16x32_bf16 v[38:41], v[170:173], v[206:209], v[38:41]
	v_mfma_f32_16x16x32_bf16 v[34:37], v[186:189], v[202:205], v[34:37]
	v_mfma_f32_16x16x32_bf16 v[34:37], v[190:193], v[206:209], v[34:37]
	v_mfma_f32_16x16x32_bf16 v[30:33], v[130:133], v[210:213], v[30:33]
	v_mfma_f32_16x16x32_bf16 v[30:33], v[134:137], v[214:217], v[30:33]
	v_mfma_f32_16x16x32_bf16 v[26:29], v[138:141], v[210:213], v[26:29]
	v_mfma_f32_16x16x32_bf16 v[26:29], v[142:145], v[214:217], v[26:29]
	v_mfma_f32_16x16x32_bf16 v[22:25], v[166:169], v[210:213], v[22:25]
	v_mfma_f32_16x16x32_bf16 v[22:25], v[170:173], v[214:217], v[22:25]
	v_mfma_f32_16x16x32_bf16 v[18:21], v[186:189], v[210:213], v[18:21]
	v_mfma_f32_16x16x32_bf16 v[18:21], v[190:193], v[214:217], v[18:21]
	v_mfma_f32_16x16x32_bf16 v[14:17], v[130:133], v[218:221], v[14:17]
	v_mfma_f32_16x16x32_bf16 v[14:17], v[134:137], v[222:225], v[14:17]
	v_mfma_f32_16x16x32_bf16 v[10:13], v[138:141], v[218:221], v[10:13]
	v_mfma_f32_16x16x32_bf16 v[10:13], v[142:145], v[222:225], v[10:13]
	v_mfma_f32_16x16x32_bf16 v[6:9], v[166:169], v[218:221], v[6:9]
	v_mfma_f32_16x16x32_bf16 v[6:9], v[170:173], v[222:225], v[6:9]
	v_mfma_f32_16x16x32_bf16 v[2:5], v[186:189], v[218:221], v[2:5]
	v_mfma_f32_16x16x32_bf16 v[2:5], v[190:193], v[222:225], v[2:5]
	s_barrier
	s_add_i32 s76, 0, 0x18000
	s_add_i32 s77, 0, 0x1c000
	ds_read_b128 v[130:133], v246
	ds_read_b128 v[134:137], v246 offset:1024
	ds_read_b128 v[138:141], v246 offset:2048
	ds_read_b128 v[142:145], v246 offset:3072
	ds_read_b128 v[166:169], v247
	ds_read_b128 v[170:173], v247 offset:1024
	ds_read_b128 v[186:189], v247 offset:2048
	ds_read_b128 v[190:193], v247 offset:3072
	s_add_u32 s74, s84, 0x100000
	s_addc_u32 s75, s85, 0
	s_mov_b32 m0, s33
	ds_read_b128 v[194:197], v177 offset:32768
	ds_read_b128 v[198:201], v177 offset:33792
	ds_read_b128 v[202:205], v177 offset:34816
	ds_read_b128 v[206:209], v177 offset:35840
	ds_read_b128 v[210:213], v177 offset:36864
	ds_read_b128 v[214:217], v177 offset:37888
	ds_read_b128 v[218:221], v177 offset:38912
	ds_read_b128 v[222:225], v177 offset:39936
	global_load_lds_dwordx4 v146, s[74:75]
	s_mov_b32 m0, s35
	s_nop 0
	global_load_lds_dwordx4 v150, s[74:75]
	s_waitcnt vmcnt(8)
	s_waitcnt lgkmcnt(0)
	s_barrier
	v_mfma_f32_16x16x32_bf16 v[126:129], v[130:133], v[194:197], v[126:129]
	v_mfma_f32_16x16x32_bf16 v[126:129], v[134:137], v[198:201], v[126:129]
	v_mfma_f32_16x16x32_bf16 v[122:125], v[138:141], v[194:197], v[122:125]
	v_mfma_f32_16x16x32_bf16 v[122:125], v[142:145], v[198:201], v[122:125]
	v_mfma_f32_16x16x32_bf16 v[118:121], v[166:169], v[194:197], v[118:121]
	v_mfma_f32_16x16x32_bf16 v[118:121], v[170:173], v[198:201], v[118:121]
	v_mfma_f32_16x16x32_bf16 v[114:117], v[186:189], v[194:197], v[114:117]
	v_mfma_f32_16x16x32_bf16 v[114:117], v[190:193], v[198:201], v[114:117]
	v_mfma_f32_16x16x32_bf16 v[110:113], v[130:133], v[202:205], v[110:113]
	v_mfma_f32_16x16x32_bf16 v[110:113], v[134:137], v[206:209], v[110:113]
	v_mfma_f32_16x16x32_bf16 v[106:109], v[138:141], v[202:205], v[106:109]
	v_mfma_f32_16x16x32_bf16 v[106:109], v[142:145], v[206:209], v[106:109]
	v_mfma_f32_16x16x32_bf16 v[102:105], v[166:169], v[202:205], v[102:105]
	v_mfma_f32_16x16x32_bf16 v[102:105], v[170:173], v[206:209], v[102:105]
	v_mfma_f32_16x16x32_bf16 v[98:101], v[186:189], v[202:205], v[98:101]
	v_mfma_f32_16x16x32_bf16 v[98:101], v[190:193], v[206:209], v[98:101]
	v_mfma_f32_16x16x32_bf16 v[94:97], v[130:133], v[210:213], v[94:97]
	v_mfma_f32_16x16x32_bf16 v[94:97], v[134:137], v[214:217], v[94:97]
	v_mfma_f32_16x16x32_bf16 v[90:93], v[138:141], v[210:213], v[90:93]
	v_mfma_f32_16x16x32_bf16 v[90:93], v[142:145], v[214:217], v[90:93]
	v_mfma_f32_16x16x32_bf16 v[86:89], v[166:169], v[210:213], v[86:89]
	v_mfma_f32_16x16x32_bf16 v[86:89], v[170:173], v[214:217], v[86:89]
	v_mfma_f32_16x16x32_bf16 v[82:85], v[186:189], v[210:213], v[82:85]
	v_mfma_f32_16x16x32_bf16 v[82:85], v[190:193], v[214:217], v[82:85]
	v_mfma_f32_16x16x32_bf16 v[78:81], v[130:133], v[218:221], v[78:81]
	v_mfma_f32_16x16x32_bf16 v[78:81], v[134:137], v[222:225], v[78:81]
	v_mfma_f32_16x16x32_bf16 v[74:77], v[138:141], v[218:221], v[74:77]
	v_mfma_f32_16x16x32_bf16 v[74:77], v[142:145], v[222:225], v[74:77]
	v_mfma_f32_16x16x32_bf16 v[70:73], v[166:169], v[218:221], v[70:73]
	v_mfma_f32_16x16x32_bf16 v[70:73], v[170:173], v[222:225], v[70:73]
	v_mfma_f32_16x16x32_bf16 v[66:69], v[186:189], v[218:221], v[66:69]
	v_mfma_f32_16x16x32_bf16 v[66:69], v[190:193], v[222:225], v[66:69]
	s_barrier
	s_add_i32 s74, s76, s3
	s_mov_b32 m0, s74
	ds_read_b128 v[194:197], v177 offset:49152
	ds_read_b128 v[198:201], v177 offset:50176
	ds_read_b128 v[202:205], v177 offset:51200
	ds_read_b128 v[206:209], v177 offset:52224
	ds_read_b128 v[210:213], v177 offset:53248
	ds_read_b128 v[214:217], v177 offset:54272
	ds_read_b128 v[218:221], v177 offset:55296
	ds_read_b128 v[222:225], v177 offset:56320
	global_load_lds_dwordx4 v148, s[98:99]
	s_add_i32 m0, s74, 0x2000
	s_add_u32 s74, s82, 0x100080
	s_addc_u32 s75, s83, 0
	s_add_i32 s76, s77, s3
	global_load_lds_dwordx4 v152, s[98:99]
	s_mov_b32 m0, s76
	s_nop 0
	global_load_lds_dwordx4 v148, s[74:75]
	s_add_i32 m0, s76, 0x2000
	s_nop 0
	global_load_lds_dwordx4 v152, s[74:75]
	s_mov_b32 m0, s62
	s_nop 0
	global_load_lds_dwordx4 v146, s[100:101]
	s_mov_b32 m0, s63
	s_nop 0
	global_load_lds_dwordx4 v150, s[100:101]
	s_waitcnt vmcnt(8)
	s_waitcnt lgkmcnt(0)
	s_barrier
	v_mfma_f32_16x16x32_bf16 v[62:65], v[130:133], v[194:197], v[62:65]
	v_mfma_f32_16x16x32_bf16 v[62:65], v[134:137], v[198:201], v[62:65]
	v_mfma_f32_16x16x32_bf16 v[58:61], v[138:141], v[194:197], v[58:61]
	v_mfma_f32_16x16x32_bf16 v[58:61], v[142:145], v[198:201], v[58:61]
	v_mfma_f32_16x16x32_bf16 v[54:57], v[166:169], v[194:197], v[54:57]
	v_mfma_f32_16x16x32_bf16 v[54:57], v[170:173], v[198:201], v[54:57]
	v_mfma_f32_16x16x32_bf16 v[50:53], v[186:189], v[194:197], v[50:53]
	v_mfma_f32_16x16x32_bf16 v[50:53], v[190:193], v[198:201], v[50:53]
	v_mfma_f32_16x16x32_bf16 v[46:49], v[130:133], v[202:205], v[46:49]
	v_mfma_f32_16x16x32_bf16 v[46:49], v[134:137], v[206:209], v[46:49]
	v_mfma_f32_16x16x32_bf16 v[42:45], v[138:141], v[202:205], v[42:45]
	v_mfma_f32_16x16x32_bf16 v[42:45], v[142:145], v[206:209], v[42:45]
	v_mfma_f32_16x16x32_bf16 v[38:41], v[166:169], v[202:205], v[38:41]
	v_mfma_f32_16x16x32_bf16 v[38:41], v[170:173], v[206:209], v[38:41]
	v_mfma_f32_16x16x32_bf16 v[34:37], v[186:189], v[202:205], v[34:37]
	v_mfma_f32_16x16x32_bf16 v[34:37], v[190:193], v[206:209], v[34:37]
	v_mfma_f32_16x16x32_bf16 v[30:33], v[130:133], v[210:213], v[30:33]
	v_mfma_f32_16x16x32_bf16 v[30:33], v[134:137], v[214:217], v[30:33]
	v_mfma_f32_16x16x32_bf16 v[26:29], v[138:141], v[210:213], v[26:29]
	v_mfma_f32_16x16x32_bf16 v[26:29], v[142:145], v[214:217], v[26:29]
	v_mfma_f32_16x16x32_bf16 v[22:25], v[166:169], v[210:213], v[22:25]
	v_mfma_f32_16x16x32_bf16 v[22:25], v[170:173], v[214:217], v[22:25]
	v_mfma_f32_16x16x32_bf16 v[18:21], v[186:189], v[210:213], v[18:21]
	v_mfma_f32_16x16x32_bf16 v[18:21], v[190:193], v[214:217], v[18:21]
	v_mfma_f32_16x16x32_bf16 v[14:17], v[130:133], v[218:221], v[14:17]
	v_mfma_f32_16x16x32_bf16 v[14:17], v[134:137], v[222:225], v[14:17]
	v_mfma_f32_16x16x32_bf16 v[10:13], v[138:141], v[218:221], v[10:13]
	v_mfma_f32_16x16x32_bf16 v[10:13], v[142:145], v[222:225], v[10:13]
	v_mfma_f32_16x16x32_bf16 v[6:9], v[166:169], v[218:221], v[6:9]
	v_mfma_f32_16x16x32_bf16 v[6:9], v[170:173], v[222:225], v[6:9]
	v_mfma_f32_16x16x32_bf16 v[2:5], v[186:189], v[218:221], v[2:5]
	v_mfma_f32_16x16x32_bf16 v[2:5], v[190:193], v[222:225], v[2:5]
	s_barrier
	s_add_i32 s73, s73, 2
	s_add_u32 s50, s50, 0x100
	s_addc_u32 s51, s51, 0
	s_add_u32 s71, s71, 0x100
	s_addc_u32 s72, s72, 0
	s_cmp_gt_u32 s73, 61
	s_cbranch_scc0 .LBB0_2109
	s_and_b64 vcc, exec, s[40:41]
	s_cbranch_vccz .LBB0_2112
	s_barrier

.LBB0_2212:
	ds_read_b128 v[150:153], v162
	ds_read_b128 v[168:171], v162 offset:1024
	ds_read_b128 v[172:175], v162 offset:2048
	ds_read_b128 v[176:179], v162 offset:3072
	ds_read_b128 v[186:189], v163
	ds_read_b128 v[190:193], v163 offset:1024
	ds_read_b128 v[194:197], v163 offset:2048
	ds_read_b128 v[198:201], v163 offset:3072
	s_add_u32 s50, s6, 0xfff00080
	s_addc_u32 s51, s7, -1
	s_cmp_eq_u32 s79, 60
	s_cselect_b32 s81, s45, s51
	s_cselect_b32 s80, s75, s50
	s_cselect_b32 s51, s43, s78
	s_cselect_b32 s50, s76, s77
	s_add_i32 m0, s33, 0xc000
	ds_read_b128 v[202:205], v164
	ds_read_b128 v[206:209], v164 offset:1024
	ds_read_b128 v[210:213], v164 offset:2048
	ds_read_b128 v[214:217], v164 offset:3072
	ds_read_b128 v[218:221], v164 offset:4096
	ds_read_b128 v[222:225], v164 offset:5120
	ds_read_b128 v[226:229], v164 offset:6144
	ds_read_b128 v[230:233], v164 offset:7168
	global_load_lds_dwordx4 v142, s[6:7]
	s_add_i32 m0, s33, 0xe000
	s_nop 0
	global_load_lds_dwordx4 v144, s[6:7]
	s_waitcnt vmcnt(8)
	s_waitcnt lgkmcnt(0)
	s_barrier
	v_mfma_f32_16x16x32_bf16 v[126:129], v[150:153], v[202:205], v[126:129]
	v_mfma_f32_16x16x32_bf16 v[126:129], v[168:171], v[206:209], v[126:129]
	v_mfma_f32_16x16x32_bf16 v[118:121], v[172:175], v[202:205], v[118:121]
	v_mfma_f32_16x16x32_bf16 v[118:121], v[176:179], v[206:209], v[118:121]
	v_mfma_f32_16x16x32_bf16 v[122:125], v[186:189], v[202:205], v[122:125]
	v_mfma_f32_16x16x32_bf16 v[122:125], v[190:193], v[206:209], v[122:125]
	v_mfma_f32_16x16x32_bf16 v[114:117], v[194:197], v[202:205], v[114:117]
	v_mfma_f32_16x16x32_bf16 v[114:117], v[198:201], v[206:209], v[114:117]
	v_mfma_f32_16x16x32_bf16 v[110:113], v[150:153], v[210:213], v[110:113]
	v_mfma_f32_16x16x32_bf16 v[110:113], v[168:171], v[214:217], v[110:113]
	v_mfma_f32_16x16x32_bf16 v[102:105], v[172:175], v[210:213], v[102:105]
	v_mfma_f32_16x16x32_bf16 v[102:105], v[176:179], v[214:217], v[102:105]
	v_mfma_f32_16x16x32_bf16 v[106:109], v[186:189], v[210:213], v[106:109]
	v_mfma_f32_16x16x32_bf16 v[106:109], v[190:193], v[214:217], v[106:109]
	v_mfma_f32_16x16x32_bf16 v[98:101], v[194:197], v[210:213], v[98:101]
	v_mfma_f32_16x16x32_bf16 v[98:101], v[198:201], v[214:217], v[98:101]
	v_mfma_f32_16x16x32_bf16 v[94:97], v[150:153], v[218:221], v[94:97]
	v_mfma_f32_16x16x32_bf16 v[94:97], v[168:171], v[222:225], v[94:97]
	v_mfma_f32_16x16x32_bf16 v[86:89], v[172:175], v[218:221], v[86:89]
	v_mfma_f32_16x16x32_bf16 v[86:89], v[176:179], v[222:225], v[86:89]
	v_mfma_f32_16x16x32_bf16 v[90:93], v[186:189], v[218:221], v[90:93]
	v_mfma_f32_16x16x32_bf16 v[90:93], v[190:193], v[222:225], v[90:93]
	v_mfma_f32_16x16x32_bf16 v[82:85], v[194:197], v[218:221], v[82:85]
	v_mfma_f32_16x16x32_bf16 v[82:85], v[198:201], v[222:225], v[82:85]
	v_mfma_f32_16x16x32_bf16 v[78:81], v[150:153], v[226:229], v[78:81]
	v_mfma_f32_16x16x32_bf16 v[78:81], v[168:171], v[230:233], v[78:81]
	v_mfma_f32_16x16x32_bf16 v[70:73], v[172:175], v[226:229], v[70:73]
	v_mfma_f32_16x16x32_bf16 v[70:73], v[176:179], v[230:233], v[70:73]
	v_mfma_f32_16x16x32_bf16 v[74:77], v[186:189], v[226:229], v[74:77]
	v_mfma_f32_16x16x32_bf16 v[74:77], v[190:193], v[230:233], v[74:77]
	v_mfma_f32_16x16x32_bf16 v[66:69], v[194:197], v[226:229], v[66:69]
	v_mfma_f32_16x16x32_bf16 v[66:69], v[198:201], v[230:233], v[66:69]
	s_barrier
	s_add_i32 s82, s68, s29
	s_add_u32 s98, s50, 0x80
	s_addc_u32 s99, s51, 0
	s_mov_b32 m0, s82
	ds_read_b128 v[202:205], v164 offset:16384
	ds_read_b128 v[206:209], v164 offset:17408
	ds_read_b128 v[210:213], v164 offset:18432
	ds_read_b128 v[214:217], v164 offset:19456
	ds_read_b128 v[218:221], v164 offset:20480
	ds_read_b128 v[222:225], v164 offset:21504
	ds_read_b128 v[226:229], v164 offset:22528
	ds_read_b128 v[230:233], v164 offset:23552
	global_load_lds_dwordx4 v134, s[50:51]
	s_add_i32 m0, s82, 0x2000
	s_add_u32 s82, s50, 0x100000
	s_addc_u32 s83, s51, 0
	s_add_i32 s84, s69, s29
	global_load_lds_dwordx4 v138, s[50:51]
	s_mov_b32 m0, s84
	global_load_lds_dwordx4 v134, s[82:83]
	s_add_i32 m0, s84, 0x2000
	s_nop 0
	global_load_lds_dwordx4 v138, s[82:83]
	s_add_u32 s100, s80, 0x80
	s_addc_u32 s101, s81, 0
	s_mov_b32 m0, s33
	s_nop 0
	global_load_lds_dwordx4 v132, s[80:81]
	s_mov_b32 m0, s35
	s_nop 0
	global_load_lds_dwordx4 v136, s[80:81]
	s_waitcnt vmcnt(8)
	s_waitcnt lgkmcnt(0)
	s_barrier
	v_mfma_f32_16x16x32_bf16 v[62:65], v[150:153], v[202:205], v[62:65]
	v_mfma_f32_16x16x32_bf16 v[62:65], v[168:171], v[206:209], v[62:65]
	v_mfma_f32_16x16x32_bf16 v[54:57], v[172:175], v[202:205], v[54:57]
	v_mfma_f32_16x16x32_bf16 v[54:57], v[176:179], v[206:209], v[54:57]
	v_mfma_f32_16x16x32_bf16 v[58:61], v[186:189], v[202:205], v[58:61]
	v_mfma_f32_16x16x32_bf16 v[58:61], v[190:193], v[206:209], v[58:61]
	v_mfma_f32_16x16x32_bf16 v[50:53], v[194:197], v[202:205], v[50:53]
	v_mfma_f32_16x16x32_bf16 v[50:53], v[198:201], v[206:209], v[50:53]
	v_mfma_f32_16x16x32_bf16 v[46:49], v[150:153], v[210:213], v[46:49]
	v_mfma_f32_16x16x32_bf16 v[46:49], v[168:171], v[214:217], v[46:49]
	v_mfma_f32_16x16x32_bf16 v[38:41], v[172:175], v[210:213], v[38:41]
	v_mfma_f32_16x16x32_bf16 v[38:41], v[176:179], v[214:217], v[38:41]
	v_mfma_f32_16x16x32_bf16 v[42:45], v[186:189], v[210:213], v[42:45]
	v_mfma_f32_16x16x32_bf16 v[42:45], v[190:193], v[214:217], v[42:45]
	v_mfma_f32_16x16x32_bf16 v[34:37], v[194:197], v[210:213], v[34:37]
	v_mfma_f32_16x16x32_bf16 v[34:37], v[198:201], v[214:217], v[34:37]
	v_mfma_f32_16x16x32_bf16 v[30:33], v[150:153], v[218:221], v[30:33]
	v_mfma_f32_16x16x32_bf16 v[30:33], v[168:171], v[222:225], v[30:33]
	v_mfma_f32_16x16x32_bf16 v[22:25], v[172:175], v[218:221], v[22:25]
	v_mfma_f32_16x16x32_bf16 v[22:25], v[176:179], v[222:225], v[22:25]
	v_mfma_f32_16x16x32_bf16 v[26:29], v[186:189], v[218:221], v[26:29]
	v_mfma_f32_16x16x32_bf16 v[26:29], v[190:193], v[222:225], v[26:29]
	v_mfma_f32_16x16x32_bf16 v[18:21], v[194:197], v[218:221], v[18:21]
	v_mfma_f32_16x16x32_bf16 v[18:21], v[198:201], v[222:225], v[18:21]
	v_mfma_f32_16x16x32_bf16 v[14:17], v[150:153], v[226:229], v[14:17]
	v_mfma_f32_16x16x32_bf16 v[14:17], v[168:171], v[230:233], v[14:17]
	v_mfma_f32_16x16x32_bf16 v[6:9], v[172:175], v[226:229], v[6:9]
	v_mfma_f32_16x16x32_bf16 v[6:9], v[176:179], v[230:233], v[6:9]
	v_mfma_f32_16x16x32_bf16 v[10:13], v[186:189], v[226:229], v[10:13]
	v_mfma_f32_16x16x32_bf16 v[10:13], v[190:193], v[230:233], v[10:13]
	v_mfma_f32_16x16x32_bf16 v[2:5], v[194:197], v[226:229], v[2:5]
	v_mfma_f32_16x16x32_bf16 v[2:5], v[198:201], v[230:233], v[2:5]
	s_barrier
	s_add_i32 s82, 0, 0x18000
	s_add_i32 s83, 0, 0x1c000
	ds_read_b128 v[150:153], v246
	ds_read_b128 v[168:171], v246 offset:1024
	ds_read_b128 v[172:175], v246 offset:2048
	ds_read_b128 v[176:179], v246 offset:3072
	ds_read_b128 v[186:189], v247
	ds_read_b128 v[190:193], v247 offset:1024
	ds_read_b128 v[194:197], v247 offset:2048
	ds_read_b128 v[198:201], v247 offset:3072
	s_add_u32 s80, s80, 0x100000
	s_addc_u32 s81, s81, 0
	s_mov_b32 m0, s59
	ds_read_b128 v[202:205], v164 offset:32768
	ds_read_b128 v[206:209], v164 offset:33792
	ds_read_b128 v[210:213], v164 offset:34816
	ds_read_b128 v[214:217], v164 offset:35840
	ds_read_b128 v[218:221], v164 offset:36864
	ds_read_b128 v[222:225], v164 offset:37888
	ds_read_b128 v[226:229], v164 offset:38912
	ds_read_b128 v[230:233], v164 offset:39936
	global_load_lds_dwordx4 v132, s[80:81]
	s_mov_b32 m0, s62
	s_nop 0
	global_load_lds_dwordx4 v136, s[80:81]
	s_waitcnt vmcnt(8)
	s_waitcnt lgkmcnt(0)
	s_barrier
	v_mfma_f32_16x16x32_bf16 v[126:129], v[150:153], v[202:205], v[126:129]
	v_mfma_f32_16x16x32_bf16 v[126:129], v[168:171], v[206:209], v[126:129]
	v_mfma_f32_16x16x32_bf16 v[118:121], v[172:175], v[202:205], v[118:121]
	v_mfma_f32_16x16x32_bf16 v[118:121], v[176:179], v[206:209], v[118:121]
	v_mfma_f32_16x16x32_bf16 v[122:125], v[186:189], v[202:205], v[122:125]
	v_mfma_f32_16x16x32_bf16 v[122:125], v[190:193], v[206:209], v[122:125]
	v_mfma_f32_16x16x32_bf16 v[114:117], v[194:197], v[202:205], v[114:117]
	v_mfma_f32_16x16x32_bf16 v[114:117], v[198:201], v[206:209], v[114:117]
	v_mfma_f32_16x16x32_bf16 v[110:113], v[150:153], v[210:213], v[110:113]
	v_mfma_f32_16x16x32_bf16 v[110:113], v[168:171], v[214:217], v[110:113]
	v_mfma_f32_16x16x32_bf16 v[102:105], v[172:175], v[210:213], v[102:105]
	v_mfma_f32_16x16x32_bf16 v[102:105], v[176:179], v[214:217], v[102:105]
	v_mfma_f32_16x16x32_bf16 v[106:109], v[186:189], v[210:213], v[106:109]
	v_mfma_f32_16x16x32_bf16 v[106:109], v[190:193], v[214:217], v[106:109]
	v_mfma_f32_16x16x32_bf16 v[98:101], v[194:197], v[210:213], v[98:101]
	v_mfma_f32_16x16x32_bf16 v[98:101], v[198:201], v[214:217], v[98:101]
	v_mfma_f32_16x16x32_bf16 v[94:97], v[150:153], v[218:221], v[94:97]
	v_mfma_f32_16x16x32_bf16 v[94:97], v[168:171], v[222:225], v[94:97]
	v_mfma_f32_16x16x32_bf16 v[86:89], v[172:175], v[218:221], v[86:89]
	v_mfma_f32_16x16x32_bf16 v[86:89], v[176:179], v[222:225], v[86:89]
	v_mfma_f32_16x16x32_bf16 v[90:93], v[186:189], v[218:221], v[90:93]
	v_mfma_f32_16x16x32_bf16 v[90:93], v[190:193], v[222:225], v[90:93]
	v_mfma_f32_16x16x32_bf16 v[82:85], v[194:197], v[218:221], v[82:85]
	v_mfma_f32_16x16x32_bf16 v[82:85], v[198:201], v[222:225], v[82:85]
	v_mfma_f32_16x16x32_bf16 v[78:81], v[150:153], v[226:229], v[78:81]
	v_mfma_f32_16x16x32_bf16 v[78:81], v[168:171], v[230:233], v[78:81]
	v_mfma_f32_16x16x32_bf16 v[70:73], v[172:175], v[226:229], v[70:73]
	v_mfma_f32_16x16x32_bf16 v[70:73], v[176:179], v[230:233], v[70:73]
	v_mfma_f32_16x16x32_bf16 v[74:77], v[186:189], v[226:229], v[74:77]
	v_mfma_f32_16x16x32_bf16 v[74:77], v[190:193], v[230:233], v[74:77]
	v_mfma_f32_16x16x32_bf16 v[66:69], v[194:197], v[226:229], v[66:69]
	v_mfma_f32_16x16x32_bf16 v[66:69], v[198:201], v[230:233], v[66:69]
	s_barrier
	s_add_i32 s80, s82, s29
	s_mov_b32 m0, s80
	ds_read_b128 v[202:205], v164 offset:49152
	ds_read_b128 v[206:209], v164 offset:50176
	ds_read_b128 v[210:213], v164 offset:51200
	ds_read_b128 v[214:217], v164 offset:52224
	ds_read_b128 v[218:221], v164 offset:53248
	ds_read_b128 v[222:225], v164 offset:54272
	ds_read_b128 v[226:229], v164 offset:55296
	ds_read_b128 v[230:233], v164 offset:56320
	global_load_lds_dwordx4 v134, s[98:99]
	s_add_i32 m0, s80, 0x2000
	s_add_u32 s50, s50, 0x100080
	s_addc_u32 s51, s51, 0
	s_add_i32 s80, s83, s29
	global_load_lds_dwordx4 v138, s[98:99]
	s_mov_b32 m0, s80
	s_nop 0
	global_load_lds_dwordx4 v134, s[50:51]
	s_add_i32 m0, s80, 0x2000
	s_nop 0
	global_load_lds_dwordx4 v138, s[50:51]
	s_mov_b32 m0, s65
	s_nop 0
	global_load_lds_dwordx4 v132, s[100:101]
	s_mov_b32 m0, s66
	s_nop 0
	global_load_lds_dwordx4 v136, s[100:101]
	s_waitcnt vmcnt(8)
	s_waitcnt lgkmcnt(0)
	s_barrier
	v_mfma_f32_16x16x32_bf16 v[62:65], v[150:153], v[202:205], v[62:65]
	v_mfma_f32_16x16x32_bf16 v[62:65], v[168:171], v[206:209], v[62:65]
	v_mfma_f32_16x16x32_bf16 v[54:57], v[172:175], v[202:205], v[54:57]
	v_mfma_f32_16x16x32_bf16 v[54:57], v[176:179], v[206:209], v[54:57]
	v_mfma_f32_16x16x32_bf16 v[58:61], v[186:189], v[202:205], v[58:61]
	v_mfma_f32_16x16x32_bf16 v[58:61], v[190:193], v[206:209], v[58:61]
	v_mfma_f32_16x16x32_bf16 v[50:53], v[194:197], v[202:205], v[50:53]
	v_mfma_f32_16x16x32_bf16 v[50:53], v[198:201], v[206:209], v[50:53]
	v_mfma_f32_16x16x32_bf16 v[46:49], v[150:153], v[210:213], v[46:49]
	v_mfma_f32_16x16x32_bf16 v[46:49], v[168:171], v[214:217], v[46:49]
	v_mfma_f32_16x16x32_bf16 v[38:41], v[172:175], v[210:213], v[38:41]
	v_mfma_f32_16x16x32_bf16 v[38:41], v[176:179], v[214:217], v[38:41]
	v_mfma_f32_16x16x32_bf16 v[42:45], v[186:189], v[210:213], v[42:45]
	v_mfma_f32_16x16x32_bf16 v[42:45], v[190:193], v[214:217], v[42:45]
	v_mfma_f32_16x16x32_bf16 v[34:37], v[194:197], v[210:213], v[34:37]
	v_mfma_f32_16x16x32_bf16 v[34:37], v[198:201], v[214:217], v[34:37]
	v_mfma_f32_16x16x32_bf16 v[30:33], v[150:153], v[218:221], v[30:33]
	v_mfma_f32_16x16x32_bf16 v[30:33], v[168:171], v[222:225], v[30:33]
	v_mfma_f32_16x16x32_bf16 v[22:25], v[172:175], v[218:221], v[22:25]
	v_mfma_f32_16x16x32_bf16 v[22:25], v[176:179], v[222:225], v[22:25]
	v_mfma_f32_16x16x32_bf16 v[26:29], v[186:189], v[218:221], v[26:29]
	v_mfma_f32_16x16x32_bf16 v[26:29], v[190:193], v[222:225], v[26:29]
	v_mfma_f32_16x16x32_bf16 v[18:21], v[194:197], v[218:221], v[18:21]
	v_mfma_f32_16x16x32_bf16 v[18:21], v[198:201], v[222:225], v[18:21]
	v_mfma_f32_16x16x32_bf16 v[14:17], v[150:153], v[226:229], v[14:17]
	v_mfma_f32_16x16x32_bf16 v[14:17], v[168:171], v[230:233], v[14:17]
	v_mfma_f32_16x16x32_bf16 v[6:9], v[172:175], v[226:229], v[6:9]
	v_mfma_f32_16x16x32_bf16 v[6:9], v[176:179], v[230:233], v[6:9]
	v_mfma_f32_16x16x32_bf16 v[10:13], v[186:189], v[226:229], v[10:13]
	v_mfma_f32_16x16x32_bf16 v[10:13], v[190:193], v[230:233], v[10:13]
	v_mfma_f32_16x16x32_bf16 v[2:5], v[194:197], v[226:229], v[2:5]
	v_mfma_f32_16x16x32_bf16 v[2:5], v[198:201], v[230:233], v[2:5]
	s_barrier
	s_add_i32 s79, s79, 2
	s_add_u32 s6, s6, 0x100
	s_addc_u32 s7, s7, 0
	s_add_u32 s77, s77, 0x100
	s_addc_u32 s78, s78, 0
	s_cmp_gt_u32 s79, 61
	s_cbranch_scc0 .LBB0_2212
	s_and_b64 vcc, exec, s[40:41]
	s_cbranch_vccz .LBB0_2215
	s_barrier

.LBB0_2340:
	ds_read_b128 v[130:133], v163
	ds_read_b128 v[134:137], v163 offset:1024
	ds_read_b128 v[138:141], v163 offset:2048
	ds_read_b128 v[142:145], v163 offset:3072
	ds_read_b128 v[146:149], v190
	ds_read_b128 v[150:153], v190 offset:1024
	ds_read_b128 v[174:177], v190 offset:2048
	ds_read_b128 v[178:181], v190 offset:3072
	s_add_u32 s42, s40, 0xffd50080
	s_addc_u32 s43, s41, -1
	s_cmpk_eq_i32 s71, 0xa8
	s_cselect_b32 s45, s1, s43
	s_cselect_b32 s44, s0, s42
	s_cselect_b32 s43, s39, s70
	s_cselect_b32 s42, s38, s12
	s_add_i32 m0, s46, 0xc000
	ds_read_b128 v[186:189], v191
	ds_read_b128 v[194:197], v191 offset:1024
	ds_read_b128 v[198:201], v191 offset:2048
	ds_read_b128 v[202:205], v191 offset:3072
	ds_read_b128 v[206:209], v191 offset:4096
	ds_read_b128 v[210:213], v191 offset:5120
	ds_read_b128 v[214:217], v191 offset:6144
	ds_read_b128 v[218:221], v191 offset:7168
	global_load_lds_dwordx4 v166, s[40:41]
	s_add_i32 m0, s46, 0xe000
	s_nop 0
	global_load_lds_dwordx4 v168, s[40:41]
	s_waitcnt vmcnt(8)
	s_waitcnt lgkmcnt(0)
	s_barrier
	v_mfma_f32_16x16x32_bf16 v[126:129], v[130:133], v[186:189], v[126:129]
	v_mfma_f32_16x16x32_bf16 v[126:129], v[134:137], v[194:197], v[126:129]
	v_mfma_f32_16x16x32_bf16 v[122:125], v[138:141], v[186:189], v[122:125]
	v_mfma_f32_16x16x32_bf16 v[122:125], v[142:145], v[194:197], v[122:125]
	v_mfma_f32_16x16x32_bf16 v[118:121], v[146:149], v[186:189], v[118:121]
	v_mfma_f32_16x16x32_bf16 v[118:121], v[150:153], v[194:197], v[118:121]
	v_mfma_f32_16x16x32_bf16 v[114:117], v[174:177], v[186:189], v[114:117]
	v_mfma_f32_16x16x32_bf16 v[114:117], v[178:181], v[194:197], v[114:117]
	v_mfma_f32_16x16x32_bf16 v[110:113], v[130:133], v[198:201], v[110:113]
	v_mfma_f32_16x16x32_bf16 v[110:113], v[134:137], v[202:205], v[110:113]
	v_mfma_f32_16x16x32_bf16 v[106:109], v[138:141], v[198:201], v[106:109]
	v_mfma_f32_16x16x32_bf16 v[106:109], v[142:145], v[202:205], v[106:109]
	v_mfma_f32_16x16x32_bf16 v[102:105], v[146:149], v[198:201], v[102:105]
	v_mfma_f32_16x16x32_bf16 v[102:105], v[150:153], v[202:205], v[102:105]
	v_mfma_f32_16x16x32_bf16 v[98:101], v[174:177], v[198:201], v[98:101]
	v_mfma_f32_16x16x32_bf16 v[98:101], v[178:181], v[202:205], v[98:101]
	v_mfma_f32_16x16x32_bf16 v[94:97], v[130:133], v[206:209], v[94:97]
	v_mfma_f32_16x16x32_bf16 v[94:97], v[134:137], v[210:213], v[94:97]
	v_mfma_f32_16x16x32_bf16 v[90:93], v[138:141], v[206:209], v[90:93]
	v_mfma_f32_16x16x32_bf16 v[90:93], v[142:145], v[210:213], v[90:93]
	v_mfma_f32_16x16x32_bf16 v[86:89], v[146:149], v[206:209], v[86:89]
	v_mfma_f32_16x16x32_bf16 v[86:89], v[150:153], v[210:213], v[86:89]
	v_mfma_f32_16x16x32_bf16 v[82:85], v[174:177], v[206:209], v[82:85]
	v_mfma_f32_16x16x32_bf16 v[82:85], v[178:181], v[210:213], v[82:85]
	v_mfma_f32_16x16x32_bf16 v[78:81], v[130:133], v[214:217], v[78:81]
	v_mfma_f32_16x16x32_bf16 v[78:81], v[134:137], v[218:221], v[78:81]
	v_mfma_f32_16x16x32_bf16 v[74:77], v[138:141], v[214:217], v[74:77]
	v_mfma_f32_16x16x32_bf16 v[74:77], v[142:145], v[218:221], v[74:77]
	v_mfma_f32_16x16x32_bf16 v[70:73], v[146:149], v[214:217], v[70:73]
	v_mfma_f32_16x16x32_bf16 v[70:73], v[150:153], v[218:221], v[70:73]
	v_mfma_f32_16x16x32_bf16 v[66:69], v[174:177], v[214:217], v[66:69]
	v_mfma_f32_16x16x32_bf16 v[66:69], v[178:181], v[218:221], v[66:69]
	s_barrier
	s_add_i32 s72, s65, s35
	s_add_u32 s98, s42, 0x80
	s_addc_u32 s99, s43, 0
	s_mov_b32 m0, s72
	ds_read_b128 v[186:189], v191 offset:16384
	ds_read_b128 v[194:197], v191 offset:17408
	ds_read_b128 v[198:201], v191 offset:18432
	ds_read_b128 v[202:205], v191 offset:19456
	ds_read_b128 v[206:209], v191 offset:20480
	ds_read_b128 v[210:213], v191 offset:21504
	ds_read_b128 v[214:217], v191 offset:22528
	ds_read_b128 v[218:221], v191 offset:23552
	global_load_lds_dwordx4 v156, s[42:43]
	s_add_i32 m0, s72, 0x2000
	s_add_u32 s72, s42, 0x2b0000
	s_addc_u32 s73, s43, 0
	s_add_i32 s74, s66, s35
	global_load_lds_dwordx4 v160, s[42:43]
	s_mov_b32 m0, s74
	global_load_lds_dwordx4 v156, s[72:73]
	s_add_i32 m0, s74, 0x2000
	s_nop 0
	global_load_lds_dwordx4 v160, s[72:73]
	s_add_u32 s100, s44, 0x80
	s_addc_u32 s101, s45, 0
	s_mov_b32 m0, s46
	s_nop 0
	global_load_lds_dwordx4 v154, s[44:45]
	s_mov_b32 m0, s47
	s_nop 0
	global_load_lds_dwordx4 v158, s[44:45]
	s_waitcnt vmcnt(8)
	s_waitcnt lgkmcnt(0)
	s_barrier
	v_mfma_f32_16x16x32_bf16 v[62:65], v[130:133], v[186:189], v[62:65]
	v_mfma_f32_16x16x32_bf16 v[62:65], v[134:137], v[194:197], v[62:65]
	v_mfma_f32_16x16x32_bf16 v[58:61], v[138:141], v[186:189], v[58:61]
	v_mfma_f32_16x16x32_bf16 v[58:61], v[142:145], v[194:197], v[58:61]
	v_mfma_f32_16x16x32_bf16 v[54:57], v[146:149], v[186:189], v[54:57]
	v_mfma_f32_16x16x32_bf16 v[54:57], v[150:153], v[194:197], v[54:57]
	v_mfma_f32_16x16x32_bf16 v[50:53], v[174:177], v[186:189], v[50:53]
	v_mfma_f32_16x16x32_bf16 v[50:53], v[178:181], v[194:197], v[50:53]
	v_mfma_f32_16x16x32_bf16 v[46:49], v[130:133], v[198:201], v[46:49]
	v_mfma_f32_16x16x32_bf16 v[46:49], v[134:137], v[202:205], v[46:49]
	v_mfma_f32_16x16x32_bf16 v[42:45], v[138:141], v[198:201], v[42:45]
	v_mfma_f32_16x16x32_bf16 v[42:45], v[142:145], v[202:205], v[42:45]
	v_mfma_f32_16x16x32_bf16 v[38:41], v[146:149], v[198:201], v[38:41]
	v_mfma_f32_16x16x32_bf16 v[38:41], v[150:153], v[202:205], v[38:41]
	v_mfma_f32_16x16x32_bf16 v[34:37], v[174:177], v[198:201], v[34:37]
	v_mfma_f32_16x16x32_bf16 v[34:37], v[178:181], v[202:205], v[34:37]
	v_mfma_f32_16x16x32_bf16 v[30:33], v[130:133], v[206:209], v[30:33]
	v_mfma_f32_16x16x32_bf16 v[30:33], v[134:137], v[210:213], v[30:33]
	v_mfma_f32_16x16x32_bf16 v[26:29], v[138:141], v[206:209], v[26:29]
	v_mfma_f32_16x16x32_bf16 v[26:29], v[142:145], v[210:213], v[26:29]
	v_mfma_f32_16x16x32_bf16 v[22:25], v[146:149], v[206:209], v[22:25]
	v_mfma_f32_16x16x32_bf16 v[22:25], v[150:153], v[210:213], v[22:25]
	v_mfma_f32_16x16x32_bf16 v[18:21], v[174:177], v[206:209], v[18:21]
	v_mfma_f32_16x16x32_bf16 v[18:21], v[178:181], v[210:213], v[18:21]
	v_mfma_f32_16x16x32_bf16 v[14:17], v[130:133], v[214:217], v[14:17]
	v_mfma_f32_16x16x32_bf16 v[14:17], v[134:137], v[218:221], v[14:17]
	v_mfma_f32_16x16x32_bf16 v[10:13], v[138:141], v[214:217], v[10:13]
	v_mfma_f32_16x16x32_bf16 v[10:13], v[142:145], v[218:221], v[10:13]
	v_mfma_f32_16x16x32_bf16 v[6:9], v[146:149], v[214:217], v[6:9]
	v_mfma_f32_16x16x32_bf16 v[6:9], v[150:153], v[218:221], v[6:9]
	v_mfma_f32_16x16x32_bf16 v[2:5], v[174:177], v[214:217], v[2:5]
	v_mfma_f32_16x16x32_bf16 v[2:5], v[178:181], v[218:221], v[2:5]
	s_barrier
	s_add_i32 s72, 0, 0x18000
	s_add_i32 s73, 0, 0x1c000
	ds_read_b128 v[130:133], v246
	ds_read_b128 v[134:137], v246 offset:1024
	ds_read_b128 v[138:141], v246 offset:2048
	ds_read_b128 v[142:145], v246 offset:3072
	ds_read_b128 v[146:149], v247
	ds_read_b128 v[150:153], v247 offset:1024
	ds_read_b128 v[174:177], v247 offset:2048
	ds_read_b128 v[178:181], v247 offset:3072
	s_add_u32 s44, s44, 0x2b0000
	s_addc_u32 s45, s45, 0
	s_mov_b32 m0, s48
	ds_read_b128 v[186:189], v191 offset:32768
	ds_read_b128 v[194:197], v191 offset:33792
	ds_read_b128 v[198:201], v191 offset:34816
	ds_read_b128 v[202:205], v191 offset:35840
	ds_read_b128 v[206:209], v191 offset:36864
	ds_read_b128 v[210:213], v191 offset:37888
	ds_read_b128 v[214:217], v191 offset:38912
	ds_read_b128 v[218:221], v191 offset:39936
	global_load_lds_dwordx4 v154, s[44:45]
	s_mov_b32 m0, s49
	s_nop 0
	global_load_lds_dwordx4 v158, s[44:45]
	s_waitcnt vmcnt(8)
	s_waitcnt lgkmcnt(0)
	s_barrier
	v_mfma_f32_16x16x32_bf16 v[126:129], v[130:133], v[186:189], v[126:129]
	v_mfma_f32_16x16x32_bf16 v[126:129], v[134:137], v[194:197], v[126:129]
	v_mfma_f32_16x16x32_bf16 v[122:125], v[138:141], v[186:189], v[122:125]
	v_mfma_f32_16x16x32_bf16 v[122:125], v[142:145], v[194:197], v[122:125]
	v_mfma_f32_16x16x32_bf16 v[118:121], v[146:149], v[186:189], v[118:121]
	v_mfma_f32_16x16x32_bf16 v[118:121], v[150:153], v[194:197], v[118:121]
	v_mfma_f32_16x16x32_bf16 v[114:117], v[174:177], v[186:189], v[114:117]
	v_mfma_f32_16x16x32_bf16 v[114:117], v[178:181], v[194:197], v[114:117]
	v_mfma_f32_16x16x32_bf16 v[110:113], v[130:133], v[198:201], v[110:113]
	v_mfma_f32_16x16x32_bf16 v[110:113], v[134:137], v[202:205], v[110:113]
	v_mfma_f32_16x16x32_bf16 v[106:109], v[138:141], v[198:201], v[106:109]
	v_mfma_f32_16x16x32_bf16 v[106:109], v[142:145], v[202:205], v[106:109]
	v_mfma_f32_16x16x32_bf16 v[102:105], v[146:149], v[198:201], v[102:105]
	v_mfma_f32_16x16x32_bf16 v[102:105], v[150:153], v[202:205], v[102:105]
	v_mfma_f32_16x16x32_bf16 v[98:101], v[174:177], v[198:201], v[98:101]
	v_mfma_f32_16x16x32_bf16 v[98:101], v[178:181], v[202:205], v[98:101]
	v_mfma_f32_16x16x32_bf16 v[94:97], v[130:133], v[206:209], v[94:97]
	v_mfma_f32_16x16x32_bf16 v[94:97], v[134:137], v[210:213], v[94:97]
	v_mfma_f32_16x16x32_bf16 v[90:93], v[138:141], v[206:209], v[90:93]
	v_mfma_f32_16x16x32_bf16 v[90:93], v[142:145], v[210:213], v[90:93]
	v_mfma_f32_16x16x32_bf16 v[86:89], v[146:149], v[206:209], v[86:89]
	v_mfma_f32_16x16x32_bf16 v[86:89], v[150:153], v[210:213], v[86:89]
	v_mfma_f32_16x16x32_bf16 v[82:85], v[174:177], v[206:209], v[82:85]
	v_mfma_f32_16x16x32_bf16 v[82:85], v[178:181], v[210:213], v[82:85]
	v_mfma_f32_16x16x32_bf16 v[78:81], v[130:133], v[214:217], v[78:81]
	v_mfma_f32_16x16x32_bf16 v[78:81], v[134:137], v[218:221], v[78:81]
	v_mfma_f32_16x16x32_bf16 v[74:77], v[138:141], v[214:217], v[74:77]
	v_mfma_f32_16x16x32_bf16 v[74:77], v[142:145], v[218:221], v[74:77]
	v_mfma_f32_16x16x32_bf16 v[70:73], v[146:149], v[214:217], v[70:73]
	v_mfma_f32_16x16x32_bf16 v[70:73], v[150:153], v[218:221], v[70:73]
	v_mfma_f32_16x16x32_bf16 v[66:69], v[174:177], v[214:217], v[66:69]
	v_mfma_f32_16x16x32_bf16 v[66:69], v[178:181], v[218:221], v[66:69]
	s_barrier
	s_add_i32 s44, s72, s35
	s_mov_b32 m0, s44
	ds_read_b128 v[186:189], v191 offset:49152
	ds_read_b128 v[194:197], v191 offset:50176
	ds_read_b128 v[198:201], v191 offset:51200
	ds_read_b128 v[202:205], v191 offset:52224
	ds_read_b128 v[206:209], v191 offset:53248
	ds_read_b128 v[210:213], v191 offset:54272
	ds_read_b128 v[214:217], v191 offset:55296
	ds_read_b128 v[218:221], v191 offset:56320
	global_load_lds_dwordx4 v156, s[98:99]
	s_add_i32 m0, s44, 0x2000
	s_add_u32 s42, s42, 0x2b0080
	s_addc_u32 s43, s43, 0
	s_add_i32 s44, s73, s35
	global_load_lds_dwordx4 v160, s[98:99]
	s_mov_b32 m0, s44
	s_nop 0
	global_load_lds_dwordx4 v156, s[42:43]
	s_add_i32 m0, s44, 0x2000
	s_nop 0
	global_load_lds_dwordx4 v160, s[42:43]
	s_mov_b32 m0, s51
	s_nop 0
	global_load_lds_dwordx4 v154, s[100:101]
	s_mov_b32 m0, s59
	s_nop 0
	global_load_lds_dwordx4 v158, s[100:101]
	s_waitcnt vmcnt(8)
	s_waitcnt lgkmcnt(0)
	s_barrier
	v_mfma_f32_16x16x32_bf16 v[62:65], v[130:133], v[186:189], v[62:65]
	v_mfma_f32_16x16x32_bf16 v[62:65], v[134:137], v[194:197], v[62:65]
	v_mfma_f32_16x16x32_bf16 v[58:61], v[138:141], v[186:189], v[58:61]
	v_mfma_f32_16x16x32_bf16 v[58:61], v[142:145], v[194:197], v[58:61]
	v_mfma_f32_16x16x32_bf16 v[54:57], v[146:149], v[186:189], v[54:57]
	v_mfma_f32_16x16x32_bf16 v[54:57], v[150:153], v[194:197], v[54:57]
	v_mfma_f32_16x16x32_bf16 v[50:53], v[174:177], v[186:189], v[50:53]
	v_mfma_f32_16x16x32_bf16 v[50:53], v[178:181], v[194:197], v[50:53]
	v_mfma_f32_16x16x32_bf16 v[46:49], v[130:133], v[198:201], v[46:49]
	v_mfma_f32_16x16x32_bf16 v[46:49], v[134:137], v[202:205], v[46:49]
	v_mfma_f32_16x16x32_bf16 v[42:45], v[138:141], v[198:201], v[42:45]
	v_mfma_f32_16x16x32_bf16 v[42:45], v[142:145], v[202:205], v[42:45]
	v_mfma_f32_16x16x32_bf16 v[38:41], v[146:149], v[198:201], v[38:41]
	v_mfma_f32_16x16x32_bf16 v[38:41], v[150:153], v[202:205], v[38:41]
	v_mfma_f32_16x16x32_bf16 v[34:37], v[174:177], v[198:201], v[34:37]
	v_mfma_f32_16x16x32_bf16 v[34:37], v[178:181], v[202:205], v[34:37]
	v_mfma_f32_16x16x32_bf16 v[30:33], v[130:133], v[206:209], v[30:33]
	v_mfma_f32_16x16x32_bf16 v[30:33], v[134:137], v[210:213], v[30:33]
	v_mfma_f32_16x16x32_bf16 v[26:29], v[138:141], v[206:209], v[26:29]
	v_mfma_f32_16x16x32_bf16 v[26:29], v[142:145], v[210:213], v[26:29]
	v_mfma_f32_16x16x32_bf16 v[22:25], v[146:149], v[206:209], v[22:25]
	v_mfma_f32_16x16x32_bf16 v[22:25], v[150:153], v[210:213], v[22:25]
	v_mfma_f32_16x16x32_bf16 v[18:21], v[174:177], v[206:209], v[18:21]
	v_mfma_f32_16x16x32_bf16 v[18:21], v[178:181], v[210:213], v[18:21]
	v_mfma_f32_16x16x32_bf16 v[14:17], v[130:133], v[214:217], v[14:17]
	v_mfma_f32_16x16x32_bf16 v[14:17], v[134:137], v[218:221], v[14:17]
	v_mfma_f32_16x16x32_bf16 v[10:13], v[138:141], v[214:217], v[10:13]
	v_mfma_f32_16x16x32_bf16 v[10:13], v[142:145], v[218:221], v[10:13]
	v_mfma_f32_16x16x32_bf16 v[6:9], v[146:149], v[214:217], v[6:9]
	v_mfma_f32_16x16x32_bf16 v[6:9], v[150:153], v[218:221], v[6:9]
	v_mfma_f32_16x16x32_bf16 v[2:5], v[174:177], v[214:217], v[2:5]
	v_mfma_f32_16x16x32_bf16 v[2:5], v[178:181], v[218:221], v[2:5]
	s_barrier
	s_add_i32 s71, s71, 2
	s_add_u32 s40, s40, 0x100
	s_addc_u32 s41, s41, 0
	s_add_u32 s12, s12, 0x100
	s_addc_u32 s70, s70, 0
	s_cmpk_gt_u32 s71, 0xa9
	s_cbranch_scc0 .LBB0_2340
	s_and_b64 vcc, exec, s[36:37]
	s_cbranch_vccz .LBB0_2343
	s_barrier

.LBB0_2464:
	ds_read_b128 v[150:153], v167
	ds_read_b128 v[172:175], v167 offset:1024
	ds_read_b128 v[176:179], v167 offset:2048
	ds_read_b128 v[184:187], v167 offset:3072
	ds_read_b128 v[188:191], v168
	ds_read_b128 v[192:195], v168 offset:1024
	ds_read_b128 v[196:199], v168 offset:2048
	ds_read_b128 v[200:203], v168 offset:3072
	s_add_u32 s74, s6, 0xfff00080
	s_addc_u32 s75, s7, -1
	s_cmp_eq_u32 s87, 60
	s_cselect_b32 s77, s47, s75
	s_cselect_b32 s76, s83, s74
	s_cselect_b32 s75, s45, s86
	s_cselect_b32 s74, s84, s85
	s_add_i32 m0, s59, 0xc000
	ds_read_b128 v[204:207], v169
	ds_read_b128 v[208:211], v169 offset:1024
	ds_read_b128 v[212:215], v169 offset:2048
	ds_read_b128 v[216:219], v169 offset:3072
	ds_read_b128 v[220:223], v169 offset:4096
	ds_read_b128 v[224:227], v169 offset:5120
	ds_read_b128 v[228:231], v169 offset:6144
	ds_read_b128 v[232:235], v169 offset:7168
	global_load_lds_dwordx4 v142, s[6:7]
	s_add_i32 m0, s59, 0xe000
	s_nop 0
	global_load_lds_dwordx4 v144, s[6:7]
	s_waitcnt vmcnt(8)
	s_waitcnt lgkmcnt(0)
	s_barrier
	v_mfma_f32_16x16x32_bf16 v[126:129], v[150:153], v[204:207], v[126:129]
	v_mfma_f32_16x16x32_bf16 v[126:129], v[172:175], v[208:211], v[126:129]
	v_mfma_f32_16x16x32_bf16 v[122:125], v[176:179], v[204:207], v[122:125]
	v_mfma_f32_16x16x32_bf16 v[122:125], v[184:187], v[208:211], v[122:125]
	v_mfma_f32_16x16x32_bf16 v[118:121], v[188:191], v[204:207], v[118:121]
	v_mfma_f32_16x16x32_bf16 v[118:121], v[192:195], v[208:211], v[118:121]
	v_mfma_f32_16x16x32_bf16 v[114:117], v[196:199], v[204:207], v[114:117]
	v_mfma_f32_16x16x32_bf16 v[114:117], v[200:203], v[208:211], v[114:117]
	v_mfma_f32_16x16x32_bf16 v[110:113], v[150:153], v[212:215], v[110:113]
	v_mfma_f32_16x16x32_bf16 v[110:113], v[172:175], v[216:219], v[110:113]
	v_mfma_f32_16x16x32_bf16 v[106:109], v[176:179], v[212:215], v[106:109]
	v_mfma_f32_16x16x32_bf16 v[106:109], v[184:187], v[216:219], v[106:109]
	v_mfma_f32_16x16x32_bf16 v[102:105], v[188:191], v[212:215], v[102:105]
	v_mfma_f32_16x16x32_bf16 v[102:105], v[192:195], v[216:219], v[102:105]
	v_mfma_f32_16x16x32_bf16 v[98:101], v[196:199], v[212:215], v[98:101]
	v_mfma_f32_16x16x32_bf16 v[98:101], v[200:203], v[216:219], v[98:101]
	v_mfma_f32_16x16x32_bf16 v[94:97], v[150:153], v[220:223], v[94:97]
	v_mfma_f32_16x16x32_bf16 v[94:97], v[172:175], v[224:227], v[94:97]
	v_mfma_f32_16x16x32_bf16 v[90:93], v[176:179], v[220:223], v[90:93]
	v_mfma_f32_16x16x32_bf16 v[90:93], v[184:187], v[224:227], v[90:93]
	v_mfma_f32_16x16x32_bf16 v[86:89], v[188:191], v[220:223], v[86:89]
	v_mfma_f32_16x16x32_bf16 v[86:89], v[192:195], v[224:227], v[86:89]
	v_mfma_f32_16x16x32_bf16 v[82:85], v[196:199], v[220:223], v[82:85]
	v_mfma_f32_16x16x32_bf16 v[82:85], v[200:203], v[224:227], v[82:85]
	v_mfma_f32_16x16x32_bf16 v[78:81], v[150:153], v[228:231], v[78:81]
	v_mfma_f32_16x16x32_bf16 v[78:81], v[172:175], v[232:235], v[78:81]
	v_mfma_f32_16x16x32_bf16 v[74:77], v[176:179], v[228:231], v[74:77]
	v_mfma_f32_16x16x32_bf16 v[74:77], v[184:187], v[232:235], v[74:77]
	v_mfma_f32_16x16x32_bf16 v[70:73], v[188:191], v[228:231], v[70:73]
	v_mfma_f32_16x16x32_bf16 v[70:73], v[192:195], v[232:235], v[70:73]
	v_mfma_f32_16x16x32_bf16 v[66:69], v[196:199], v[228:231], v[66:69]
	v_mfma_f32_16x16x32_bf16 v[66:69], v[200:203], v[232:235], v[66:69]
	s_barrier
	s_add_i32 s88, s70, s27
	s_add_u32 s98, s74, 0x80
	s_addc_u32 s99, s75, 0
	s_mov_b32 m0, s88
	ds_read_b128 v[204:207], v169 offset:16384
	ds_read_b128 v[208:211], v169 offset:17408
	ds_read_b128 v[212:215], v169 offset:18432
	ds_read_b128 v[216:219], v169 offset:19456
	ds_read_b128 v[220:223], v169 offset:20480
	ds_read_b128 v[224:227], v169 offset:21504
	ds_read_b128 v[228:231], v169 offset:22528
	ds_read_b128 v[232:235], v169 offset:23552
	global_load_lds_dwordx4 v132, s[74:75]
	s_add_i32 m0, s88, 0x2000
	s_add_u32 s88, s74, 0x100000
	s_addc_u32 s89, s75, 0
	s_add_i32 s90, s71, s27
	global_load_lds_dwordx4 v136, s[74:75]
	s_mov_b32 m0, s90
	global_load_lds_dwordx4 v132, s[88:89]
	s_add_i32 m0, s90, 0x2000
	s_nop 0
	global_load_lds_dwordx4 v136, s[88:89]
	s_add_u32 s100, s76, 0x80
	s_addc_u32 s101, s77, 0
	s_mov_b32 m0, s59
	s_nop 0
	global_load_lds_dwordx4 v130, s[76:77]
	s_mov_b32 m0, s62
	s_nop 0
	global_load_lds_dwordx4 v134, s[76:77]
	s_waitcnt vmcnt(8)
	s_waitcnt lgkmcnt(0)
	s_barrier
	v_mfma_f32_16x16x32_bf16 v[62:65], v[150:153], v[204:207], v[62:65]
	v_mfma_f32_16x16x32_bf16 v[62:65], v[172:175], v[208:211], v[62:65]
	v_mfma_f32_16x16x32_bf16 v[58:61], v[176:179], v[204:207], v[58:61]
	v_mfma_f32_16x16x32_bf16 v[58:61], v[184:187], v[208:211], v[58:61]
	v_mfma_f32_16x16x32_bf16 v[54:57], v[188:191], v[204:207], v[54:57]
	v_mfma_f32_16x16x32_bf16 v[54:57], v[192:195], v[208:211], v[54:57]
	v_mfma_f32_16x16x32_bf16 v[46:49], v[196:199], v[204:207], v[46:49]
	v_mfma_f32_16x16x32_bf16 v[46:49], v[200:203], v[208:211], v[46:49]
	v_mfma_f32_16x16x32_bf16 v[50:53], v[150:153], v[212:215], v[50:53]
	v_mfma_f32_16x16x32_bf16 v[50:53], v[172:175], v[216:219], v[50:53]
	v_mfma_f32_16x16x32_bf16 v[42:45], v[176:179], v[212:215], v[42:45]
	v_mfma_f32_16x16x32_bf16 v[42:45], v[184:187], v[216:219], v[42:45]
	v_mfma_f32_16x16x32_bf16 v[38:41], v[188:191], v[212:215], v[38:41]
	v_mfma_f32_16x16x32_bf16 v[38:41], v[192:195], v[216:219], v[38:41]
	v_mfma_f32_16x16x32_bf16 v[30:33], v[196:199], v[212:215], v[30:33]
	v_mfma_f32_16x16x32_bf16 v[30:33], v[200:203], v[216:219], v[30:33]
	v_mfma_f32_16x16x32_bf16 v[34:37], v[150:153], v[220:223], v[34:37]
	v_mfma_f32_16x16x32_bf16 v[34:37], v[172:175], v[224:227], v[34:37]
	v_mfma_f32_16x16x32_bf16 v[26:29], v[176:179], v[220:223], v[26:29]
	v_mfma_f32_16x16x32_bf16 v[26:29], v[184:187], v[224:227], v[26:29]
	v_mfma_f32_16x16x32_bf16 v[22:25], v[188:191], v[220:223], v[22:25]
	v_mfma_f32_16x16x32_bf16 v[22:25], v[192:195], v[224:227], v[22:25]
	v_mfma_f32_16x16x32_bf16 v[14:17], v[196:199], v[220:223], v[14:17]
	v_mfma_f32_16x16x32_bf16 v[14:17], v[200:203], v[224:227], v[14:17]
	v_mfma_f32_16x16x32_bf16 v[18:21], v[150:153], v[228:231], v[18:21]
	v_mfma_f32_16x16x32_bf16 v[18:21], v[172:175], v[232:235], v[18:21]
	v_mfma_f32_16x16x32_bf16 v[10:13], v[176:179], v[228:231], v[10:13]
	v_mfma_f32_16x16x32_bf16 v[10:13], v[184:187], v[232:235], v[10:13]
	v_mfma_f32_16x16x32_bf16 v[6:9], v[188:191], v[228:231], v[6:9]
	v_mfma_f32_16x16x32_bf16 v[6:9], v[192:195], v[232:235], v[6:9]
	v_mfma_f32_16x16x32_bf16 v[2:5], v[196:199], v[228:231], v[2:5]
	v_mfma_f32_16x16x32_bf16 v[2:5], v[200:203], v[232:235], v[2:5]
	s_barrier
	s_add_i32 s88, 0, 0x18000
	s_add_i32 s89, 0, 0x1c000
	ds_read_b128 v[150:153], v246
	ds_read_b128 v[172:175], v246 offset:1024
	ds_read_b128 v[176:179], v246 offset:2048
	ds_read_b128 v[184:187], v246 offset:3072
	ds_read_b128 v[188:191], v247
	ds_read_b128 v[192:195], v247 offset:1024
	ds_read_b128 v[196:199], v247 offset:2048
	ds_read_b128 v[200:203], v247 offset:3072
	s_add_u32 s76, s76, 0x100000
	s_addc_u32 s77, s77, 0
	s_mov_b32 m0, s63
	ds_read_b128 v[204:207], v169 offset:32768
	ds_read_b128 v[208:211], v169 offset:33792
	ds_read_b128 v[212:215], v169 offset:34816
	ds_read_b128 v[216:219], v169 offset:35840
	ds_read_b128 v[220:223], v169 offset:36864
	ds_read_b128 v[224:227], v169 offset:37888
	ds_read_b128 v[228:231], v169 offset:38912
	ds_read_b128 v[232:235], v169 offset:39936
	global_load_lds_dwordx4 v130, s[76:77]
	s_mov_b32 m0, s65
	s_nop 0
	global_load_lds_dwordx4 v134, s[76:77]
	s_waitcnt vmcnt(8)
	s_waitcnt lgkmcnt(0)
	s_barrier
	v_mfma_f32_16x16x32_bf16 v[126:129], v[150:153], v[204:207], v[126:129]
	v_mfma_f32_16x16x32_bf16 v[126:129], v[172:175], v[208:211], v[126:129]
	v_mfma_f32_16x16x32_bf16 v[122:125], v[176:179], v[204:207], v[122:125]
	v_mfma_f32_16x16x32_bf16 v[122:125], v[184:187], v[208:211], v[122:125]
	v_mfma_f32_16x16x32_bf16 v[118:121], v[188:191], v[204:207], v[118:121]
	v_mfma_f32_16x16x32_bf16 v[118:121], v[192:195], v[208:211], v[118:121]
	v_mfma_f32_16x16x32_bf16 v[114:117], v[196:199], v[204:207], v[114:117]
	v_mfma_f32_16x16x32_bf16 v[114:117], v[200:203], v[208:211], v[114:117]
	v_mfma_f32_16x16x32_bf16 v[110:113], v[150:153], v[212:215], v[110:113]
	v_mfma_f32_16x16x32_bf16 v[110:113], v[172:175], v[216:219], v[110:113]
	v_mfma_f32_16x16x32_bf16 v[106:109], v[176:179], v[212:215], v[106:109]
	v_mfma_f32_16x16x32_bf16 v[106:109], v[184:187], v[216:219], v[106:109]
	v_mfma_f32_16x16x32_bf16 v[102:105], v[188:191], v[212:215], v[102:105]
	v_mfma_f32_16x16x32_bf16 v[102:105], v[192:195], v[216:219], v[102:105]
	v_mfma_f32_16x16x32_bf16 v[98:101], v[196:199], v[212:215], v[98:101]
	v_mfma_f32_16x16x32_bf16 v[98:101], v[200:203], v[216:219], v[98:101]
	v_mfma_f32_16x16x32_bf16 v[94:97], v[150:153], v[220:223], v[94:97]
	v_mfma_f32_16x16x32_bf16 v[94:97], v[172:175], v[224:227], v[94:97]
	v_mfma_f32_16x16x32_bf16 v[90:93], v[176:179], v[220:223], v[90:93]
	v_mfma_f32_16x16x32_bf16 v[90:93], v[184:187], v[224:227], v[90:93]
	v_mfma_f32_16x16x32_bf16 v[86:89], v[188:191], v[220:223], v[86:89]
	v_mfma_f32_16x16x32_bf16 v[86:89], v[192:195], v[224:227], v[86:89]
	v_mfma_f32_16x16x32_bf16 v[82:85], v[196:199], v[220:223], v[82:85]
	v_mfma_f32_16x16x32_bf16 v[82:85], v[200:203], v[224:227], v[82:85]
	v_mfma_f32_16x16x32_bf16 v[78:81], v[150:153], v[228:231], v[78:81]
	v_mfma_f32_16x16x32_bf16 v[78:81], v[172:175], v[232:235], v[78:81]
	v_mfma_f32_16x16x32_bf16 v[74:77], v[176:179], v[228:231], v[74:77]
	v_mfma_f32_16x16x32_bf16 v[74:77], v[184:187], v[232:235], v[74:77]
	v_mfma_f32_16x16x32_bf16 v[70:73], v[188:191], v[228:231], v[70:73]
	v_mfma_f32_16x16x32_bf16 v[70:73], v[192:195], v[232:235], v[70:73]
	v_mfma_f32_16x16x32_bf16 v[66:69], v[196:199], v[228:231], v[66:69]
	v_mfma_f32_16x16x32_bf16 v[66:69], v[200:203], v[232:235], v[66:69]
	s_barrier
	s_add_i32 s76, s88, s27
	s_mov_b32 m0, s76
	ds_read_b128 v[204:207], v169 offset:49152
	ds_read_b128 v[208:211], v169 offset:50176
	ds_read_b128 v[212:215], v169 offset:51200
	ds_read_b128 v[216:219], v169 offset:52224
	ds_read_b128 v[220:223], v169 offset:53248
	ds_read_b128 v[224:227], v169 offset:54272
	ds_read_b128 v[228:231], v169 offset:55296
	ds_read_b128 v[232:235], v169 offset:56320
	global_load_lds_dwordx4 v132, s[98:99]
	s_add_i32 m0, s76, 0x2000
	s_add_u32 s74, s74, 0x100080
	s_addc_u32 s75, s75, 0
	s_add_i32 s76, s89, s27
	global_load_lds_dwordx4 v136, s[98:99]
	s_mov_b32 m0, s76
	s_nop 0
	global_load_lds_dwordx4 v132, s[74:75]
	s_add_i32 m0, s76, 0x2000
	s_nop 0
	global_load_lds_dwordx4 v136, s[74:75]
	s_mov_b32 m0, s67
	s_nop 0
	global_load_lds_dwordx4 v130, s[100:101]
	s_mov_b32 m0, s68
	s_nop 0
	global_load_lds_dwordx4 v134, s[100:101]
	s_waitcnt vmcnt(8)
	s_waitcnt lgkmcnt(0)
	s_barrier
	v_mfma_f32_16x16x32_bf16 v[62:65], v[150:153], v[204:207], v[62:65]
	v_mfma_f32_16x16x32_bf16 v[62:65], v[172:175], v[208:211], v[62:65]
	v_mfma_f32_16x16x32_bf16 v[58:61], v[176:179], v[204:207], v[58:61]
	v_mfma_f32_16x16x32_bf16 v[58:61], v[184:187], v[208:211], v[58:61]
	v_mfma_f32_16x16x32_bf16 v[54:57], v[188:191], v[204:207], v[54:57]
	v_mfma_f32_16x16x32_bf16 v[54:57], v[192:195], v[208:211], v[54:57]
	v_mfma_f32_16x16x32_bf16 v[46:49], v[196:199], v[204:207], v[46:49]
	v_mfma_f32_16x16x32_bf16 v[46:49], v[200:203], v[208:211], v[46:49]
	v_mfma_f32_16x16x32_bf16 v[50:53], v[150:153], v[212:215], v[50:53]
	v_mfma_f32_16x16x32_bf16 v[50:53], v[172:175], v[216:219], v[50:53]
	v_mfma_f32_16x16x32_bf16 v[42:45], v[176:179], v[212:215], v[42:45]
	v_mfma_f32_16x16x32_bf16 v[42:45], v[184:187], v[216:219], v[42:45]
	v_mfma_f32_16x16x32_bf16 v[38:41], v[188:191], v[212:215], v[38:41]
	v_mfma_f32_16x16x32_bf16 v[38:41], v[192:195], v[216:219], v[38:41]
	v_mfma_f32_16x16x32_bf16 v[30:33], v[196:199], v[212:215], v[30:33]
	v_mfma_f32_16x16x32_bf16 v[30:33], v[200:203], v[216:219], v[30:33]
	v_mfma_f32_16x16x32_bf16 v[34:37], v[150:153], v[220:223], v[34:37]
	v_mfma_f32_16x16x32_bf16 v[34:37], v[172:175], v[224:227], v[34:37]
	v_mfma_f32_16x16x32_bf16 v[26:29], v[176:179], v[220:223], v[26:29]
	v_mfma_f32_16x16x32_bf16 v[26:29], v[184:187], v[224:227], v[26:29]
	v_mfma_f32_16x16x32_bf16 v[22:25], v[188:191], v[220:223], v[22:25]
	v_mfma_f32_16x16x32_bf16 v[22:25], v[192:195], v[224:227], v[22:25]
	v_mfma_f32_16x16x32_bf16 v[14:17], v[196:199], v[220:223], v[14:17]
	v_mfma_f32_16x16x32_bf16 v[14:17], v[200:203], v[224:227], v[14:17]
	v_mfma_f32_16x16x32_bf16 v[18:21], v[150:153], v[228:231], v[18:21]
	v_mfma_f32_16x16x32_bf16 v[18:21], v[172:175], v[232:235], v[18:21]
	v_mfma_f32_16x16x32_bf16 v[10:13], v[176:179], v[228:231], v[10:13]
	v_mfma_f32_16x16x32_bf16 v[10:13], v[184:187], v[232:235], v[10:13]
	v_mfma_f32_16x16x32_bf16 v[6:9], v[188:191], v[228:231], v[6:9]
	v_mfma_f32_16x16x32_bf16 v[6:9], v[192:195], v[232:235], v[6:9]
	v_mfma_f32_16x16x32_bf16 v[2:5], v[196:199], v[228:231], v[2:5]
	v_mfma_f32_16x16x32_bf16 v[2:5], v[200:203], v[232:235], v[2:5]
	s_barrier
	s_add_i32 s87, s87, 2
	s_add_u32 s6, s6, 0x100
	s_addc_u32 s7, s7, 0
	s_add_u32 s85, s85, 0x100
	s_addc_u32 s86, s86, 0
	s_cmp_gt_u32 s87, 61
	s_cbranch_scc0 .LBB0_2464
	s_and_b64 vcc, exec, s[38:39]
	s_cbranch_vccz .LBB0_2467
	s_barrier

.LBB0_2494:
	ds_read_b128 v[160:163], v155
	ds_read_b128 v[164:167], v155 offset:1024
	ds_read_b128 v[168:171], v155 offset:2048
	ds_read_b128 v[172:175], v155 offset:3072
	ds_read_b128 v[176:179], v156
	ds_read_b128 v[184:187], v156 offset:1024
	ds_read_b128 v[188:191], v156 offset:2048
	ds_read_b128 v[192:195], v156 offset:3072
	s_add_u32 s48, s6, 0xfff00080
	s_addc_u32 s49, s7, -1
	s_cmp_eq_u32 s89, 60
	s_cselect_b32 s51, s43, s49
	s_cselect_b32 s50, s85, s48
	s_cselect_b32 s49, s41, s88
	s_cselect_b32 s48, s86, s87
	s_add_i32 m0, s63, 0xc000
	ds_read_b128 v[196:199], v157
	ds_read_b128 v[200:203], v157 offset:1024
	ds_read_b128 v[204:207], v157 offset:2048
	ds_read_b128 v[208:211], v157 offset:3072
	ds_read_b128 v[212:215], v157 offset:4096
	ds_read_b128 v[216:219], v157 offset:5120
	ds_read_b128 v[220:223], v157 offset:6144
	ds_read_b128 v[224:227], v157 offset:7168
	global_load_lds_dwordx4 v140, s[6:7]
	s_add_i32 m0, s63, 0xe000
	s_nop 0
	global_load_lds_dwordx4 v142, s[6:7]
	s_waitcnt vmcnt(8)
	s_waitcnt lgkmcnt(0)
	s_barrier
	v_mfma_f32_16x16x32_bf16 v[126:129], v[160:163], v[196:199], v[126:129]
	v_mfma_f32_16x16x32_bf16 v[126:129], v[164:167], v[200:203], v[126:129]
	v_mfma_f32_16x16x32_bf16 v[122:125], v[168:171], v[196:199], v[122:125]
	v_mfma_f32_16x16x32_bf16 v[122:125], v[172:175], v[200:203], v[122:125]
	v_mfma_f32_16x16x32_bf16 v[118:121], v[176:179], v[196:199], v[118:121]
	v_mfma_f32_16x16x32_bf16 v[118:121], v[184:187], v[200:203], v[118:121]
	v_mfma_f32_16x16x32_bf16 v[114:117], v[188:191], v[196:199], v[114:117]
	v_mfma_f32_16x16x32_bf16 v[114:117], v[192:195], v[200:203], v[114:117]
	v_mfma_f32_16x16x32_bf16 v[110:113], v[160:163], v[204:207], v[110:113]
	v_mfma_f32_16x16x32_bf16 v[110:113], v[164:167], v[208:211], v[110:113]
	v_mfma_f32_16x16x32_bf16 v[106:109], v[168:171], v[204:207], v[106:109]
	v_mfma_f32_16x16x32_bf16 v[106:109], v[172:175], v[208:211], v[106:109]
	v_mfma_f32_16x16x32_bf16 v[102:105], v[176:179], v[204:207], v[102:105]
	v_mfma_f32_16x16x32_bf16 v[102:105], v[184:187], v[208:211], v[102:105]
	v_mfma_f32_16x16x32_bf16 v[98:101], v[188:191], v[204:207], v[98:101]
	v_mfma_f32_16x16x32_bf16 v[98:101], v[192:195], v[208:211], v[98:101]
	v_mfma_f32_16x16x32_bf16 v[94:97], v[160:163], v[212:215], v[94:97]
	v_mfma_f32_16x16x32_bf16 v[94:97], v[164:167], v[216:219], v[94:97]
	v_mfma_f32_16x16x32_bf16 v[90:93], v[168:171], v[212:215], v[90:93]
	v_mfma_f32_16x16x32_bf16 v[90:93], v[172:175], v[216:219], v[90:93]
	v_mfma_f32_16x16x32_bf16 v[86:89], v[176:179], v[212:215], v[86:89]
	v_mfma_f32_16x16x32_bf16 v[86:89], v[184:187], v[216:219], v[86:89]
	v_mfma_f32_16x16x32_bf16 v[82:85], v[188:191], v[212:215], v[82:85]
	v_mfma_f32_16x16x32_bf16 v[82:85], v[192:195], v[216:219], v[82:85]
	v_mfma_f32_16x16x32_bf16 v[78:81], v[160:163], v[220:223], v[78:81]
	v_mfma_f32_16x16x32_bf16 v[78:81], v[164:167], v[224:227], v[78:81]
	v_mfma_f32_16x16x32_bf16 v[74:77], v[168:171], v[220:223], v[74:77]
	v_mfma_f32_16x16x32_bf16 v[74:77], v[172:175], v[224:227], v[74:77]
	v_mfma_f32_16x16x32_bf16 v[70:73], v[176:179], v[220:223], v[70:73]
	v_mfma_f32_16x16x32_bf16 v[70:73], v[184:187], v[224:227], v[70:73]
	v_mfma_f32_16x16x32_bf16 v[66:69], v[188:191], v[220:223], v[66:69]
	v_mfma_f32_16x16x32_bf16 v[66:69], v[192:195], v[224:227], v[66:69]
	s_barrier
	s_add_i32 s90, s73, s27
	s_add_u32 s98, s48, 0x80
	s_addc_u32 s99, s49, 0
	s_mov_b32 m0, s90
	ds_read_b128 v[196:199], v157 offset:16384
	ds_read_b128 v[200:203], v157 offset:17408
	ds_read_b128 v[204:207], v157 offset:18432
	ds_read_b128 v[208:211], v157 offset:19456
	ds_read_b128 v[212:215], v157 offset:20480
	ds_read_b128 v[216:219], v157 offset:21504
	ds_read_b128 v[220:223], v157 offset:22528
	ds_read_b128 v[224:227], v157 offset:23552
	global_load_lds_dwordx4 v132, s[48:49]
	s_add_i32 m0, s90, 0x2000
	s_add_u32 s90, s48, 0x100000
	s_addc_u32 s91, s49, 0
	s_add_i32 s92, s74, s27
	global_load_lds_dwordx4 v136, s[48:49]
	s_mov_b32 m0, s92
	global_load_lds_dwordx4 v132, s[90:91]
	s_add_i32 m0, s92, 0x2000
	s_nop 0
	global_load_lds_dwordx4 v136, s[90:91]
	s_add_u32 s100, s50, 0x80
	s_addc_u32 s101, s51, 0
	s_mov_b32 m0, s63
	s_nop 0
	global_load_lds_dwordx4 v130, s[50:51]
	s_mov_b32 m0, s65
	s_nop 0
	global_load_lds_dwordx4 v134, s[50:51]
	s_waitcnt vmcnt(8)
	s_waitcnt lgkmcnt(0)
	s_barrier
	v_mfma_f32_16x16x32_bf16 v[62:65], v[160:163], v[196:199], v[62:65]
	v_mfma_f32_16x16x32_bf16 v[62:65], v[164:167], v[200:203], v[62:65]
	v_mfma_f32_16x16x32_bf16 v[58:61], v[168:171], v[196:199], v[58:61]
	v_mfma_f32_16x16x32_bf16 v[58:61], v[172:175], v[200:203], v[58:61]
	v_mfma_f32_16x16x32_bf16 v[54:57], v[176:179], v[196:199], v[54:57]
	v_mfma_f32_16x16x32_bf16 v[54:57], v[184:187], v[200:203], v[54:57]
	v_mfma_f32_16x16x32_bf16 v[46:49], v[188:191], v[196:199], v[46:49]
	v_mfma_f32_16x16x32_bf16 v[46:49], v[192:195], v[200:203], v[46:49]
	v_mfma_f32_16x16x32_bf16 v[50:53], v[160:163], v[204:207], v[50:53]
	v_mfma_f32_16x16x32_bf16 v[50:53], v[164:167], v[208:211], v[50:53]
	v_mfma_f32_16x16x32_bf16 v[42:45], v[168:171], v[204:207], v[42:45]
	v_mfma_f32_16x16x32_bf16 v[42:45], v[172:175], v[208:211], v[42:45]
	v_mfma_f32_16x16x32_bf16 v[38:41], v[176:179], v[204:207], v[38:41]
	v_mfma_f32_16x16x32_bf16 v[38:41], v[184:187], v[208:211], v[38:41]
	v_mfma_f32_16x16x32_bf16 v[30:33], v[188:191], v[204:207], v[30:33]
	v_mfma_f32_16x16x32_bf16 v[30:33], v[192:195], v[208:211], v[30:33]
	v_mfma_f32_16x16x32_bf16 v[34:37], v[160:163], v[212:215], v[34:37]
	v_mfma_f32_16x16x32_bf16 v[34:37], v[164:167], v[216:219], v[34:37]
	v_mfma_f32_16x16x32_bf16 v[26:29], v[168:171], v[212:215], v[26:29]
	v_mfma_f32_16x16x32_bf16 v[26:29], v[172:175], v[216:219], v[26:29]
	v_mfma_f32_16x16x32_bf16 v[22:25], v[176:179], v[212:215], v[22:25]
	v_mfma_f32_16x16x32_bf16 v[22:25], v[184:187], v[216:219], v[22:25]
	v_mfma_f32_16x16x32_bf16 v[14:17], v[188:191], v[212:215], v[14:17]
	v_mfma_f32_16x16x32_bf16 v[14:17], v[192:195], v[216:219], v[14:17]
	v_mfma_f32_16x16x32_bf16 v[18:21], v[160:163], v[220:223], v[18:21]
	v_mfma_f32_16x16x32_bf16 v[18:21], v[164:167], v[224:227], v[18:21]
	v_mfma_f32_16x16x32_bf16 v[10:13], v[168:171], v[220:223], v[10:13]
	v_mfma_f32_16x16x32_bf16 v[10:13], v[172:175], v[224:227], v[10:13]
	v_mfma_f32_16x16x32_bf16 v[6:9], v[176:179], v[220:223], v[6:9]
	v_mfma_f32_16x16x32_bf16 v[6:9], v[184:187], v[224:227], v[6:9]
	v_mfma_f32_16x16x32_bf16 v[2:5], v[188:191], v[220:223], v[2:5]
	v_mfma_f32_16x16x32_bf16 v[2:5], v[192:195], v[224:227], v[2:5]
	s_barrier
	s_add_i32 s90, 0, 0x18000
	s_add_i32 s91, 0, 0x1c000
	ds_read_b128 v[160:163], v246
	ds_read_b128 v[164:167], v246 offset:1024
	ds_read_b128 v[168:171], v246 offset:2048
	ds_read_b128 v[172:175], v246 offset:3072
	ds_read_b128 v[176:179], v247
	ds_read_b128 v[184:187], v247 offset:1024
	ds_read_b128 v[188:191], v247 offset:2048
	ds_read_b128 v[192:195], v247 offset:3072
	s_add_u32 s50, s50, 0x100000
	s_addc_u32 s51, s51, 0
	s_mov_b32 m0, s66
	ds_read_b128 v[196:199], v157 offset:32768
	ds_read_b128 v[200:203], v157 offset:33792
	ds_read_b128 v[204:207], v157 offset:34816
	ds_read_b128 v[208:211], v157 offset:35840
	ds_read_b128 v[212:215], v157 offset:36864
	ds_read_b128 v[216:219], v157 offset:37888
	ds_read_b128 v[220:223], v157 offset:38912
	ds_read_b128 v[224:227], v157 offset:39936
	global_load_lds_dwordx4 v130, s[50:51]
	s_mov_b32 m0, s67
	s_nop 0
	global_load_lds_dwordx4 v134, s[50:51]
	s_waitcnt vmcnt(8)
	s_waitcnt lgkmcnt(0)
	s_barrier
	v_mfma_f32_16x16x32_bf16 v[126:129], v[160:163], v[196:199], v[126:129]
	v_mfma_f32_16x16x32_bf16 v[126:129], v[164:167], v[200:203], v[126:129]
	v_mfma_f32_16x16x32_bf16 v[122:125], v[168:171], v[196:199], v[122:125]
	v_mfma_f32_16x16x32_bf16 v[122:125], v[172:175], v[200:203], v[122:125]
	v_mfma_f32_16x16x32_bf16 v[118:121], v[176:179], v[196:199], v[118:121]
	v_mfma_f32_16x16x32_bf16 v[118:121], v[184:187], v[200:203], v[118:121]
	v_mfma_f32_16x16x32_bf16 v[114:117], v[188:191], v[196:199], v[114:117]
	v_mfma_f32_16x16x32_bf16 v[114:117], v[192:195], v[200:203], v[114:117]
	v_mfma_f32_16x16x32_bf16 v[110:113], v[160:163], v[204:207], v[110:113]
	v_mfma_f32_16x16x32_bf16 v[110:113], v[164:167], v[208:211], v[110:113]
	v_mfma_f32_16x16x32_bf16 v[106:109], v[168:171], v[204:207], v[106:109]
	v_mfma_f32_16x16x32_bf16 v[106:109], v[172:175], v[208:211], v[106:109]
	v_mfma_f32_16x16x32_bf16 v[102:105], v[176:179], v[204:207], v[102:105]
	v_mfma_f32_16x16x32_bf16 v[102:105], v[184:187], v[208:211], v[102:105]
	v_mfma_f32_16x16x32_bf16 v[98:101], v[188:191], v[204:207], v[98:101]
	v_mfma_f32_16x16x32_bf16 v[98:101], v[192:195], v[208:211], v[98:101]
	v_mfma_f32_16x16x32_bf16 v[94:97], v[160:163], v[212:215], v[94:97]
	v_mfma_f32_16x16x32_bf16 v[94:97], v[164:167], v[216:219], v[94:97]
	v_mfma_f32_16x16x32_bf16 v[90:93], v[168:171], v[212:215], v[90:93]
	v_mfma_f32_16x16x32_bf16 v[90:93], v[172:175], v[216:219], v[90:93]
	v_mfma_f32_16x16x32_bf16 v[86:89], v[176:179], v[212:215], v[86:89]
	v_mfma_f32_16x16x32_bf16 v[86:89], v[184:187], v[216:219], v[86:89]
	v_mfma_f32_16x16x32_bf16 v[82:85], v[188:191], v[212:215], v[82:85]
	v_mfma_f32_16x16x32_bf16 v[82:85], v[192:195], v[216:219], v[82:85]
	v_mfma_f32_16x16x32_bf16 v[78:81], v[160:163], v[220:223], v[78:81]
	v_mfma_f32_16x16x32_bf16 v[78:81], v[164:167], v[224:227], v[78:81]
	v_mfma_f32_16x16x32_bf16 v[74:77], v[168:171], v[220:223], v[74:77]
	v_mfma_f32_16x16x32_bf16 v[74:77], v[172:175], v[224:227], v[74:77]
	v_mfma_f32_16x16x32_bf16 v[70:73], v[176:179], v[220:223], v[70:73]
	v_mfma_f32_16x16x32_bf16 v[70:73], v[184:187], v[224:227], v[70:73]
	v_mfma_f32_16x16x32_bf16 v[66:69], v[188:191], v[220:223], v[66:69]
	v_mfma_f32_16x16x32_bf16 v[66:69], v[192:195], v[224:227], v[66:69]
	s_barrier
	s_add_i32 s50, s90, s27
	s_mov_b32 m0, s50
	ds_read_b128 v[196:199], v157 offset:49152
	ds_read_b128 v[200:203], v157 offset:50176
	ds_read_b128 v[204:207], v157 offset:51200
	ds_read_b128 v[208:211], v157 offset:52224
	ds_read_b128 v[212:215], v157 offset:53248
	ds_read_b128 v[216:219], v157 offset:54272
	ds_read_b128 v[220:223], v157 offset:55296
	ds_read_b128 v[224:227], v157 offset:56320
	global_load_lds_dwordx4 v132, s[98:99]
	s_add_i32 m0, s50, 0x2000
	s_add_u32 s48, s48, 0x100080
	s_addc_u32 s49, s49, 0
	s_add_i32 s50, s91, s27
	global_load_lds_dwordx4 v136, s[98:99]
	s_mov_b32 m0, s50
	s_nop 0
	global_load_lds_dwordx4 v132, s[48:49]
	s_add_i32 m0, s50, 0x2000
	s_nop 0
	global_load_lds_dwordx4 v136, s[48:49]
	s_mov_b32 m0, s69
	s_nop 0
	global_load_lds_dwordx4 v130, s[100:101]
	s_mov_b32 m0, s70
	s_nop 0
	global_load_lds_dwordx4 v134, s[100:101]
	s_waitcnt vmcnt(8)
	s_waitcnt lgkmcnt(0)
	s_barrier
	v_mfma_f32_16x16x32_bf16 v[62:65], v[160:163], v[196:199], v[62:65]
	v_mfma_f32_16x16x32_bf16 v[62:65], v[164:167], v[200:203], v[62:65]
	v_mfma_f32_16x16x32_bf16 v[58:61], v[168:171], v[196:199], v[58:61]
	v_mfma_f32_16x16x32_bf16 v[58:61], v[172:175], v[200:203], v[58:61]
	v_mfma_f32_16x16x32_bf16 v[54:57], v[176:179], v[196:199], v[54:57]
	v_mfma_f32_16x16x32_bf16 v[54:57], v[184:187], v[200:203], v[54:57]
	v_mfma_f32_16x16x32_bf16 v[46:49], v[188:191], v[196:199], v[46:49]
	v_mfma_f32_16x16x32_bf16 v[46:49], v[192:195], v[200:203], v[46:49]
	v_mfma_f32_16x16x32_bf16 v[50:53], v[160:163], v[204:207], v[50:53]
	v_mfma_f32_16x16x32_bf16 v[50:53], v[164:167], v[208:211], v[50:53]
	v_mfma_f32_16x16x32_bf16 v[42:45], v[168:171], v[204:207], v[42:45]
	v_mfma_f32_16x16x32_bf16 v[42:45], v[172:175], v[208:211], v[42:45]
	v_mfma_f32_16x16x32_bf16 v[38:41], v[176:179], v[204:207], v[38:41]
	v_mfma_f32_16x16x32_bf16 v[38:41], v[184:187], v[208:211], v[38:41]
	v_mfma_f32_16x16x32_bf16 v[30:33], v[188:191], v[204:207], v[30:33]
	v_mfma_f32_16x16x32_bf16 v[30:33], v[192:195], v[208:211], v[30:33]
	v_mfma_f32_16x16x32_bf16 v[34:37], v[160:163], v[212:215], v[34:37]
	v_mfma_f32_16x16x32_bf16 v[34:37], v[164:167], v[216:219], v[34:37]
	v_mfma_f32_16x16x32_bf16 v[26:29], v[168:171], v[212:215], v[26:29]
	v_mfma_f32_16x16x32_bf16 v[26:29], v[172:175], v[216:219], v[26:29]
	v_mfma_f32_16x16x32_bf16 v[22:25], v[176:179], v[212:215], v[22:25]
	v_mfma_f32_16x16x32_bf16 v[22:25], v[184:187], v[216:219], v[22:25]
	v_mfma_f32_16x16x32_bf16 v[14:17], v[188:191], v[212:215], v[14:17]
	v_mfma_f32_16x16x32_bf16 v[14:17], v[192:195], v[216:219], v[14:17]
	v_mfma_f32_16x16x32_bf16 v[18:21], v[160:163], v[220:223], v[18:21]
	v_mfma_f32_16x16x32_bf16 v[18:21], v[164:167], v[224:227], v[18:21]
	v_mfma_f32_16x16x32_bf16 v[10:13], v[168:171], v[220:223], v[10:13]
	v_mfma_f32_16x16x32_bf16 v[10:13], v[172:175], v[224:227], v[10:13]
	v_mfma_f32_16x16x32_bf16 v[6:9], v[176:179], v[220:223], v[6:9]
	v_mfma_f32_16x16x32_bf16 v[6:9], v[184:187], v[224:227], v[6:9]
	v_mfma_f32_16x16x32_bf16 v[2:5], v[188:191], v[220:223], v[2:5]
	v_mfma_f32_16x16x32_bf16 v[2:5], v[192:195], v[224:227], v[2:5]
	s_barrier
	s_add_i32 s89, s89, 2
	s_add_u32 s6, s6, 0x100
	s_addc_u32 s7, s7, 0
	s_add_u32 s87, s87, 0x100
	s_addc_u32 s88, s88, 0
	s_cmp_gt_u32 s89, 61
	s_cbranch_scc0 .LBB0_2494
	s_and_b64 vcc, exec, s[38:39]
	s_cbranch_vccz .LBB0_2497
	s_barrier

.LBB0_2635:
	ds_read_b128 v[130:133], v163
	ds_read_b128 v[134:137], v163 offset:1024
	ds_read_b128 v[138:141], v163 offset:2048
	ds_read_b128 v[142:145], v163 offset:3072
	ds_read_b128 v[146:149], v188
	ds_read_b128 v[150:153], v188 offset:1024
	ds_read_b128 v[174:177], v188 offset:2048
	ds_read_b128 v[178:181], v188 offset:3072
	s_add_u32 s48, s46, 0xfff00080
	s_addc_u32 s49, s47, -1
	s_cmp_eq_u32 s73, 60
	s_cselect_b32 s51, s22, s49
	s_cselect_b32 s50, s41, s48
	s_cselect_b32 s49, s39, s72
	s_cselect_b32 s48, s70, s71
	s_add_i32 m0, s13, 0xc000
	ds_read_b128 v[184:187], v189
	ds_read_b128 v[192:195], v189 offset:1024
	ds_read_b128 v[196:199], v189 offset:2048
	ds_read_b128 v[200:203], v189 offset:3072
	ds_read_b128 v[204:207], v189 offset:4096
	ds_read_b128 v[208:211], v189 offset:5120
	ds_read_b128 v[212:215], v189 offset:6144
	ds_read_b128 v[216:219], v189 offset:7168
	global_load_lds_dwordx4 v166, s[46:47]
	s_add_i32 m0, s13, 0xe000
	s_nop 0
	global_load_lds_dwordx4 v168, s[46:47]
	s_waitcnt vmcnt(8)
	s_waitcnt lgkmcnt(0)
	s_barrier
	v_mfma_f32_16x16x32_bf16 v[126:129], v[130:133], v[184:187], v[126:129]
	v_mfma_f32_16x16x32_bf16 v[126:129], v[134:137], v[192:195], v[126:129]
	v_mfma_f32_16x16x32_bf16 v[122:125], v[138:141], v[184:187], v[122:125]
	v_mfma_f32_16x16x32_bf16 v[122:125], v[142:145], v[192:195], v[122:125]
	v_mfma_f32_16x16x32_bf16 v[118:121], v[146:149], v[184:187], v[118:121]
	v_mfma_f32_16x16x32_bf16 v[118:121], v[150:153], v[192:195], v[118:121]
	v_mfma_f32_16x16x32_bf16 v[114:117], v[174:177], v[184:187], v[114:117]
	v_mfma_f32_16x16x32_bf16 v[114:117], v[178:181], v[192:195], v[114:117]
	v_mfma_f32_16x16x32_bf16 v[110:113], v[130:133], v[196:199], v[110:113]
	v_mfma_f32_16x16x32_bf16 v[110:113], v[134:137], v[200:203], v[110:113]
	v_mfma_f32_16x16x32_bf16 v[106:109], v[138:141], v[196:199], v[106:109]
	v_mfma_f32_16x16x32_bf16 v[106:109], v[142:145], v[200:203], v[106:109]
	v_mfma_f32_16x16x32_bf16 v[102:105], v[146:149], v[196:199], v[102:105]
	v_mfma_f32_16x16x32_bf16 v[102:105], v[150:153], v[200:203], v[102:105]
	v_mfma_f32_16x16x32_bf16 v[98:101], v[174:177], v[196:199], v[98:101]
	v_mfma_f32_16x16x32_bf16 v[98:101], v[178:181], v[200:203], v[98:101]
	v_mfma_f32_16x16x32_bf16 v[94:97], v[130:133], v[204:207], v[94:97]
	v_mfma_f32_16x16x32_bf16 v[94:97], v[134:137], v[208:211], v[94:97]
	v_mfma_f32_16x16x32_bf16 v[90:93], v[138:141], v[204:207], v[90:93]
	v_mfma_f32_16x16x32_bf16 v[90:93], v[142:145], v[208:211], v[90:93]
	v_mfma_f32_16x16x32_bf16 v[86:89], v[146:149], v[204:207], v[86:89]
	v_mfma_f32_16x16x32_bf16 v[86:89], v[150:153], v[208:211], v[86:89]
	v_mfma_f32_16x16x32_bf16 v[82:85], v[174:177], v[204:207], v[82:85]
	v_mfma_f32_16x16x32_bf16 v[82:85], v[178:181], v[208:211], v[82:85]
	v_mfma_f32_16x16x32_bf16 v[78:81], v[130:133], v[212:215], v[78:81]
	v_mfma_f32_16x16x32_bf16 v[78:81], v[134:137], v[216:219], v[78:81]
	v_mfma_f32_16x16x32_bf16 v[74:77], v[138:141], v[212:215], v[74:77]
	v_mfma_f32_16x16x32_bf16 v[74:77], v[142:145], v[216:219], v[74:77]
	v_mfma_f32_16x16x32_bf16 v[70:73], v[146:149], v[212:215], v[70:73]
	v_mfma_f32_16x16x32_bf16 v[70:73], v[150:153], v[216:219], v[70:73]
	v_mfma_f32_16x16x32_bf16 v[66:69], v[174:177], v[212:215], v[66:69]
	v_mfma_f32_16x16x32_bf16 v[66:69], v[178:181], v[216:219], v[66:69]
	s_barrier
	s_add_i32 s74, s67, s3
	s_add_u32 s98, s48, 0x80
	s_addc_u32 s99, s49, 0
	s_mov_b32 m0, s74
	ds_read_b128 v[184:187], v189 offset:16384
	ds_read_b128 v[192:195], v189 offset:17408
	ds_read_b128 v[196:199], v189 offset:18432
	ds_read_b128 v[200:203], v189 offset:19456
	ds_read_b128 v[204:207], v189 offset:20480
	ds_read_b128 v[208:211], v189 offset:21504
	ds_read_b128 v[212:215], v189 offset:22528
	ds_read_b128 v[216:219], v189 offset:23552
	global_load_lds_dwordx4 v156, s[48:49]
	s_add_i32 m0, s74, 0x2000
	s_add_u32 s74, s48, 0x100000
	s_addc_u32 s75, s49, 0
	s_add_i32 s76, s68, s3
	global_load_lds_dwordx4 v160, s[48:49]
	s_mov_b32 m0, s76
	global_load_lds_dwordx4 v156, s[74:75]
	s_add_i32 m0, s76, 0x2000
	s_nop 0
	global_load_lds_dwordx4 v160, s[74:75]
	s_add_u32 s100, s50, 0x80
	s_addc_u32 s101, s51, 0
	s_mov_b32 m0, s13
	s_nop 0
	global_load_lds_dwordx4 v154, s[50:51]
	s_mov_b32 m0, s21
	s_nop 0
	global_load_lds_dwordx4 v158, s[50:51]
	s_waitcnt vmcnt(8)
	s_waitcnt lgkmcnt(0)
	s_barrier
	v_mfma_f32_16x16x32_bf16 v[62:65], v[130:133], v[184:187], v[62:65]
	v_mfma_f32_16x16x32_bf16 v[62:65], v[134:137], v[192:195], v[62:65]
	v_mfma_f32_16x16x32_bf16 v[58:61], v[138:141], v[184:187], v[58:61]
	v_mfma_f32_16x16x32_bf16 v[58:61], v[142:145], v[192:195], v[58:61]
	v_mfma_f32_16x16x32_bf16 v[54:57], v[146:149], v[184:187], v[54:57]
	v_mfma_f32_16x16x32_bf16 v[54:57], v[150:153], v[192:195], v[54:57]
	v_mfma_f32_16x16x32_bf16 v[50:53], v[174:177], v[184:187], v[50:53]
	v_mfma_f32_16x16x32_bf16 v[50:53], v[178:181], v[192:195], v[50:53]
	v_mfma_f32_16x16x32_bf16 v[46:49], v[130:133], v[196:199], v[46:49]
	v_mfma_f32_16x16x32_bf16 v[46:49], v[134:137], v[200:203], v[46:49]
	v_mfma_f32_16x16x32_bf16 v[42:45], v[138:141], v[196:199], v[42:45]
	v_mfma_f32_16x16x32_bf16 v[42:45], v[142:145], v[200:203], v[42:45]
	v_mfma_f32_16x16x32_bf16 v[38:41], v[146:149], v[196:199], v[38:41]
	v_mfma_f32_16x16x32_bf16 v[38:41], v[150:153], v[200:203], v[38:41]
	v_mfma_f32_16x16x32_bf16 v[34:37], v[174:177], v[196:199], v[34:37]
	v_mfma_f32_16x16x32_bf16 v[34:37], v[178:181], v[200:203], v[34:37]
	v_mfma_f32_16x16x32_bf16 v[30:33], v[130:133], v[204:207], v[30:33]
	v_mfma_f32_16x16x32_bf16 v[30:33], v[134:137], v[208:211], v[30:33]
	v_mfma_f32_16x16x32_bf16 v[26:29], v[138:141], v[204:207], v[26:29]
	v_mfma_f32_16x16x32_bf16 v[26:29], v[142:145], v[208:211], v[26:29]
	v_mfma_f32_16x16x32_bf16 v[22:25], v[146:149], v[204:207], v[22:25]
	v_mfma_f32_16x16x32_bf16 v[22:25], v[150:153], v[208:211], v[22:25]
	v_mfma_f32_16x16x32_bf16 v[18:21], v[174:177], v[204:207], v[18:21]
	v_mfma_f32_16x16x32_bf16 v[18:21], v[178:181], v[208:211], v[18:21]
	v_mfma_f32_16x16x32_bf16 v[14:17], v[130:133], v[212:215], v[14:17]
	v_mfma_f32_16x16x32_bf16 v[14:17], v[134:137], v[216:219], v[14:17]
	v_mfma_f32_16x16x32_bf16 v[10:13], v[138:141], v[212:215], v[10:13]
	v_mfma_f32_16x16x32_bf16 v[10:13], v[142:145], v[216:219], v[10:13]
	v_mfma_f32_16x16x32_bf16 v[6:9], v[146:149], v[212:215], v[6:9]
	v_mfma_f32_16x16x32_bf16 v[6:9], v[150:153], v[216:219], v[6:9]
	v_mfma_f32_16x16x32_bf16 v[2:5], v[174:177], v[212:215], v[2:5]
	v_mfma_f32_16x16x32_bf16 v[2:5], v[178:181], v[216:219], v[2:5]
	s_barrier
	s_add_i32 s74, 0, 0x18000
	s_add_i32 s75, 0, 0x1c000
	ds_read_b128 v[130:133], v246
	ds_read_b128 v[134:137], v246 offset:1024
	ds_read_b128 v[138:141], v246 offset:2048
	ds_read_b128 v[142:145], v246 offset:3072
	ds_read_b128 v[146:149], v247
	ds_read_b128 v[150:153], v247 offset:1024
	ds_read_b128 v[174:177], v247 offset:2048
	ds_read_b128 v[178:181], v247 offset:3072
	s_add_u32 s50, s50, 0x100000
	s_addc_u32 s51, s51, 0
	s_mov_b32 m0, s33
	ds_read_b128 v[184:187], v189 offset:32768
	ds_read_b128 v[192:195], v189 offset:33792
	ds_read_b128 v[196:199], v189 offset:34816
	ds_read_b128 v[200:203], v189 offset:35840
	ds_read_b128 v[204:207], v189 offset:36864
	ds_read_b128 v[208:211], v189 offset:37888
	ds_read_b128 v[212:215], v189 offset:38912
	ds_read_b128 v[216:219], v189 offset:39936
	global_load_lds_dwordx4 v154, s[50:51]
	s_mov_b32 m0, s35
	s_nop 0
	global_load_lds_dwordx4 v158, s[50:51]
	s_waitcnt vmcnt(8)
	s_waitcnt lgkmcnt(0)
	s_barrier
	v_mfma_f32_16x16x32_bf16 v[126:129], v[130:133], v[184:187], v[126:129]
	v_mfma_f32_16x16x32_bf16 v[126:129], v[134:137], v[192:195], v[126:129]
	v_mfma_f32_16x16x32_bf16 v[122:125], v[138:141], v[184:187], v[122:125]
	v_mfma_f32_16x16x32_bf16 v[122:125], v[142:145], v[192:195], v[122:125]
	v_mfma_f32_16x16x32_bf16 v[118:121], v[146:149], v[184:187], v[118:121]
	v_mfma_f32_16x16x32_bf16 v[118:121], v[150:153], v[192:195], v[118:121]
	v_mfma_f32_16x16x32_bf16 v[114:117], v[174:177], v[184:187], v[114:117]
	v_mfma_f32_16x16x32_bf16 v[114:117], v[178:181], v[192:195], v[114:117]
	v_mfma_f32_16x16x32_bf16 v[110:113], v[130:133], v[196:199], v[110:113]
	v_mfma_f32_16x16x32_bf16 v[110:113], v[134:137], v[200:203], v[110:113]
	v_mfma_f32_16x16x32_bf16 v[106:109], v[138:141], v[196:199], v[106:109]
	v_mfma_f32_16x16x32_bf16 v[106:109], v[142:145], v[200:203], v[106:109]
	v_mfma_f32_16x16x32_bf16 v[102:105], v[146:149], v[196:199], v[102:105]
	v_mfma_f32_16x16x32_bf16 v[102:105], v[150:153], v[200:203], v[102:105]
	v_mfma_f32_16x16x32_bf16 v[98:101], v[174:177], v[196:199], v[98:101]
	v_mfma_f32_16x16x32_bf16 v[98:101], v[178:181], v[200:203], v[98:101]
	v_mfma_f32_16x16x32_bf16 v[94:97], v[130:133], v[204:207], v[94:97]
	v_mfma_f32_16x16x32_bf16 v[94:97], v[134:137], v[208:211], v[94:97]
	v_mfma_f32_16x16x32_bf16 v[90:93], v[138:141], v[204:207], v[90:93]
	v_mfma_f32_16x16x32_bf16 v[90:93], v[142:145], v[208:211], v[90:93]
	v_mfma_f32_16x16x32_bf16 v[86:89], v[146:149], v[204:207], v[86:89]
	v_mfma_f32_16x16x32_bf16 v[86:89], v[150:153], v[208:211], v[86:89]
	v_mfma_f32_16x16x32_bf16 v[82:85], v[174:177], v[204:207], v[82:85]
	v_mfma_f32_16x16x32_bf16 v[82:85], v[178:181], v[208:211], v[82:85]
	v_mfma_f32_16x16x32_bf16 v[78:81], v[130:133], v[212:215], v[78:81]
	v_mfma_f32_16x16x32_bf16 v[78:81], v[134:137], v[216:219], v[78:81]
	v_mfma_f32_16x16x32_bf16 v[74:77], v[138:141], v[212:215], v[74:77]
	v_mfma_f32_16x16x32_bf16 v[74:77], v[142:145], v[216:219], v[74:77]
	v_mfma_f32_16x16x32_bf16 v[70:73], v[146:149], v[212:215], v[70:73]
	v_mfma_f32_16x16x32_bf16 v[70:73], v[150:153], v[216:219], v[70:73]
	v_mfma_f32_16x16x32_bf16 v[66:69], v[174:177], v[212:215], v[66:69]
	v_mfma_f32_16x16x32_bf16 v[66:69], v[178:181], v[216:219], v[66:69]
	s_barrier
	s_add_i32 s50, s74, s3
	s_mov_b32 m0, s50
	ds_read_b128 v[184:187], v189 offset:49152
	ds_read_b128 v[192:195], v189 offset:50176
	ds_read_b128 v[196:199], v189 offset:51200
	ds_read_b128 v[200:203], v189 offset:52224
	ds_read_b128 v[204:207], v189 offset:53248
	ds_read_b128 v[208:211], v189 offset:54272
	ds_read_b128 v[212:215], v189 offset:55296
	ds_read_b128 v[216:219], v189 offset:56320
	global_load_lds_dwordx4 v156, s[98:99]
	s_add_i32 m0, s50, 0x2000
	s_add_u32 s48, s48, 0x100080
	s_addc_u32 s49, s49, 0
	s_add_i32 s50, s75, s3
	global_load_lds_dwordx4 v160, s[98:99]
	s_mov_b32 m0, s50
	s_nop 0
	global_load_lds_dwordx4 v156, s[48:49]
	s_add_i32 m0, s50, 0x2000
	s_nop 0
	global_load_lds_dwordx4 v160, s[48:49]
	s_mov_b32 m0, s62
	s_nop 0
	global_load_lds_dwordx4 v154, s[100:101]
	s_mov_b32 m0, s63
	s_nop 0
	global_load_lds_dwordx4 v158, s[100:101]
	s_waitcnt vmcnt(8)
	s_waitcnt lgkmcnt(0)
	s_barrier
	v_mfma_f32_16x16x32_bf16 v[62:65], v[130:133], v[184:187], v[62:65]
	v_mfma_f32_16x16x32_bf16 v[62:65], v[134:137], v[192:195], v[62:65]
	v_mfma_f32_16x16x32_bf16 v[58:61], v[138:141], v[184:187], v[58:61]
	v_mfma_f32_16x16x32_bf16 v[58:61], v[142:145], v[192:195], v[58:61]
	v_mfma_f32_16x16x32_bf16 v[54:57], v[146:149], v[184:187], v[54:57]
	v_mfma_f32_16x16x32_bf16 v[54:57], v[150:153], v[192:195], v[54:57]
	v_mfma_f32_16x16x32_bf16 v[50:53], v[174:177], v[184:187], v[50:53]
	v_mfma_f32_16x16x32_bf16 v[50:53], v[178:181], v[192:195], v[50:53]
	v_mfma_f32_16x16x32_bf16 v[46:49], v[130:133], v[196:199], v[46:49]
	v_mfma_f32_16x16x32_bf16 v[46:49], v[134:137], v[200:203], v[46:49]
	v_mfma_f32_16x16x32_bf16 v[42:45], v[138:141], v[196:199], v[42:45]
	v_mfma_f32_16x16x32_bf16 v[42:45], v[142:145], v[200:203], v[42:45]
	v_mfma_f32_16x16x32_bf16 v[38:41], v[146:149], v[196:199], v[38:41]
	v_mfma_f32_16x16x32_bf16 v[38:41], v[150:153], v[200:203], v[38:41]
	v_mfma_f32_16x16x32_bf16 v[34:37], v[174:177], v[196:199], v[34:37]
	v_mfma_f32_16x16x32_bf16 v[34:37], v[178:181], v[200:203], v[34:37]
	v_mfma_f32_16x16x32_bf16 v[30:33], v[130:133], v[204:207], v[30:33]
	v_mfma_f32_16x16x32_bf16 v[30:33], v[134:137], v[208:211], v[30:33]
	v_mfma_f32_16x16x32_bf16 v[26:29], v[138:141], v[204:207], v[26:29]
	v_mfma_f32_16x16x32_bf16 v[26:29], v[142:145], v[208:211], v[26:29]
	v_mfma_f32_16x16x32_bf16 v[22:25], v[146:149], v[204:207], v[22:25]
	v_mfma_f32_16x16x32_bf16 v[22:25], v[150:153], v[208:211], v[22:25]
	v_mfma_f32_16x16x32_bf16 v[18:21], v[174:177], v[204:207], v[18:21]
	v_mfma_f32_16x16x32_bf16 v[18:21], v[178:181], v[208:211], v[18:21]
	v_mfma_f32_16x16x32_bf16 v[14:17], v[130:133], v[212:215], v[14:17]
	v_mfma_f32_16x16x32_bf16 v[14:17], v[134:137], v[216:219], v[14:17]
	v_mfma_f32_16x16x32_bf16 v[10:13], v[138:141], v[212:215], v[10:13]
	v_mfma_f32_16x16x32_bf16 v[10:13], v[142:145], v[216:219], v[10:13]
	v_mfma_f32_16x16x32_bf16 v[6:9], v[146:149], v[212:215], v[6:9]
	v_mfma_f32_16x16x32_bf16 v[6:9], v[150:153], v[216:219], v[6:9]
	v_mfma_f32_16x16x32_bf16 v[2:5], v[174:177], v[212:215], v[2:5]
	v_mfma_f32_16x16x32_bf16 v[2:5], v[178:181], v[216:219], v[2:5]
	s_barrier
	s_add_i32 s73, s73, 2
	s_add_u32 s46, s46, 0x100
	s_addc_u32 s47, s47, 0
	s_add_u32 s71, s71, 0x100
	s_addc_u32 s72, s72, 0
	s_cmp_gt_u32 s73, 61
	s_cbranch_scc0 .LBB0_2635
	s_and_b64 vcc, exec, s[36:37]
	s_cbranch_vccz .LBB0_2638
	s_barrier

.LBB0_2720:
	ds_read_b128 v[148:151], v159
	ds_read_b128 v[164:167], v159 offset:1024
	ds_read_b128 v[168:171], v159 offset:2048
	ds_read_b128 v[172:175], v159 offset:3072
	ds_read_b128 v[176:179], v160
	ds_read_b128 v[184:187], v160 offset:1024
	ds_read_b128 v[188:191], v160 offset:2048
	ds_read_b128 v[192:195], v160 offset:3072
	s_add_u32 s40, s6, 0xfff00080
	s_addc_u32 s41, s7, -1
	s_cmp_eq_u32 s82, 60
	s_cselect_b32 s43, s29, s41
	s_cselect_b32 s42, s78, s40
	s_cselect_b32 s41, s27, s81
	s_cselect_b32 s40, s79, s80
	s_add_i32 m0, s44, 0xc000
	ds_read_b128 v[196:199], v161
	ds_read_b128 v[200:203], v161 offset:1024
	ds_read_b128 v[204:207], v161 offset:2048
	ds_read_b128 v[208:211], v161 offset:3072
	ds_read_b128 v[212:215], v161 offset:4096
	ds_read_b128 v[216:219], v161 offset:5120
	ds_read_b128 v[220:223], v161 offset:6144
	ds_read_b128 v[224:227], v161 offset:7168
	global_load_lds_dwordx4 v140, s[6:7]
	s_add_i32 m0, s44, 0xe000
	s_nop 0
	global_load_lds_dwordx4 v142, s[6:7]
	s_waitcnt vmcnt(8)
	s_waitcnt lgkmcnt(0)
	s_barrier
	v_mfma_f32_16x16x32_bf16 v[126:129], v[148:151], v[196:199], v[126:129]
	v_mfma_f32_16x16x32_bf16 v[126:129], v[164:167], v[200:203], v[126:129]
	v_mfma_f32_16x16x32_bf16 v[118:121], v[168:171], v[196:199], v[118:121]
	v_mfma_f32_16x16x32_bf16 v[118:121], v[172:175], v[200:203], v[118:121]
	v_mfma_f32_16x16x32_bf16 v[122:125], v[176:179], v[196:199], v[122:125]
	v_mfma_f32_16x16x32_bf16 v[122:125], v[184:187], v[200:203], v[122:125]
	v_mfma_f32_16x16x32_bf16 v[114:117], v[188:191], v[196:199], v[114:117]
	v_mfma_f32_16x16x32_bf16 v[114:117], v[192:195], v[200:203], v[114:117]
	v_mfma_f32_16x16x32_bf16 v[110:113], v[148:151], v[204:207], v[110:113]
	v_mfma_f32_16x16x32_bf16 v[110:113], v[164:167], v[208:211], v[110:113]
	v_mfma_f32_16x16x32_bf16 v[102:105], v[168:171], v[204:207], v[102:105]
	v_mfma_f32_16x16x32_bf16 v[102:105], v[172:175], v[208:211], v[102:105]
	v_mfma_f32_16x16x32_bf16 v[106:109], v[176:179], v[204:207], v[106:109]
	v_mfma_f32_16x16x32_bf16 v[106:109], v[184:187], v[208:211], v[106:109]
	v_mfma_f32_16x16x32_bf16 v[98:101], v[188:191], v[204:207], v[98:101]
	v_mfma_f32_16x16x32_bf16 v[98:101], v[192:195], v[208:211], v[98:101]
	v_mfma_f32_16x16x32_bf16 v[94:97], v[148:151], v[212:215], v[94:97]
	v_mfma_f32_16x16x32_bf16 v[94:97], v[164:167], v[216:219], v[94:97]
	v_mfma_f32_16x16x32_bf16 v[86:89], v[168:171], v[212:215], v[86:89]
	v_mfma_f32_16x16x32_bf16 v[86:89], v[172:175], v[216:219], v[86:89]
	v_mfma_f32_16x16x32_bf16 v[90:93], v[176:179], v[212:215], v[90:93]
	v_mfma_f32_16x16x32_bf16 v[90:93], v[184:187], v[216:219], v[90:93]
	v_mfma_f32_16x16x32_bf16 v[82:85], v[188:191], v[212:215], v[82:85]
	v_mfma_f32_16x16x32_bf16 v[82:85], v[192:195], v[216:219], v[82:85]
	v_mfma_f32_16x16x32_bf16 v[78:81], v[148:151], v[220:223], v[78:81]
	v_mfma_f32_16x16x32_bf16 v[78:81], v[164:167], v[224:227], v[78:81]
	v_mfma_f32_16x16x32_bf16 v[70:73], v[168:171], v[220:223], v[70:73]
	v_mfma_f32_16x16x32_bf16 v[70:73], v[172:175], v[224:227], v[70:73]
	v_mfma_f32_16x16x32_bf16 v[74:77], v[176:179], v[220:223], v[74:77]
	v_mfma_f32_16x16x32_bf16 v[74:77], v[184:187], v[224:227], v[74:77]
	v_mfma_f32_16x16x32_bf16 v[66:69], v[188:191], v[220:223], v[66:69]
	v_mfma_f32_16x16x32_bf16 v[66:69], v[192:195], v[224:227], v[66:69]
	s_barrier
	s_add_i32 s83, s68, s13
	s_add_u32 s98, s40, 0x80
	s_addc_u32 s99, s41, 0
	s_mov_b32 m0, s83
	ds_read_b128 v[196:199], v161 offset:16384
	ds_read_b128 v[200:203], v161 offset:17408
	ds_read_b128 v[204:207], v161 offset:18432
	ds_read_b128 v[208:211], v161 offset:19456
	ds_read_b128 v[212:215], v161 offset:20480
	ds_read_b128 v[216:219], v161 offset:21504
	ds_read_b128 v[220:223], v161 offset:22528
	ds_read_b128 v[224:227], v161 offset:23552
	global_load_lds_dwordx4 v132, s[40:41]
	s_add_i32 m0, s83, 0x2000
	s_add_u32 s84, s40, 0x100000
	s_addc_u32 s85, s41, 0
	s_add_i32 s83, s69, s13
	global_load_lds_dwordx4 v136, s[40:41]
	s_mov_b32 m0, s83
	global_load_lds_dwordx4 v132, s[84:85]
	s_add_i32 m0, s83, 0x2000
	s_nop 0
	global_load_lds_dwordx4 v136, s[84:85]
	s_add_u32 s100, s42, 0x80
	s_addc_u32 s101, s43, 0
	s_mov_b32 m0, s44
	s_nop 0
	global_load_lds_dwordx4 v130, s[42:43]
	s_mov_b32 m0, s45
	s_nop 0
	global_load_lds_dwordx4 v134, s[42:43]
	s_waitcnt vmcnt(8)
	s_waitcnt lgkmcnt(0)
	s_barrier
	v_mfma_f32_16x16x32_bf16 v[62:65], v[148:151], v[196:199], v[62:65]
	v_mfma_f32_16x16x32_bf16 v[62:65], v[164:167], v[200:203], v[62:65]
	v_mfma_f32_16x16x32_bf16 v[54:57], v[168:171], v[196:199], v[54:57]
	v_mfma_f32_16x16x32_bf16 v[54:57], v[172:175], v[200:203], v[54:57]
	v_mfma_f32_16x16x32_bf16 v[58:61], v[176:179], v[196:199], v[58:61]
	v_mfma_f32_16x16x32_bf16 v[58:61], v[184:187], v[200:203], v[58:61]
	v_mfma_f32_16x16x32_bf16 v[50:53], v[188:191], v[196:199], v[50:53]
	v_mfma_f32_16x16x32_bf16 v[50:53], v[192:195], v[200:203], v[50:53]
	v_mfma_f32_16x16x32_bf16 v[46:49], v[148:151], v[204:207], v[46:49]
	v_mfma_f32_16x16x32_bf16 v[46:49], v[164:167], v[208:211], v[46:49]
	v_mfma_f32_16x16x32_bf16 v[38:41], v[168:171], v[204:207], v[38:41]
	v_mfma_f32_16x16x32_bf16 v[38:41], v[172:175], v[208:211], v[38:41]
	v_mfma_f32_16x16x32_bf16 v[42:45], v[176:179], v[204:207], v[42:45]
	v_mfma_f32_16x16x32_bf16 v[42:45], v[184:187], v[208:211], v[42:45]
	v_mfma_f32_16x16x32_bf16 v[34:37], v[188:191], v[204:207], v[34:37]
	v_mfma_f32_16x16x32_bf16 v[34:37], v[192:195], v[208:211], v[34:37]
	v_mfma_f32_16x16x32_bf16 v[30:33], v[148:151], v[212:215], v[30:33]
	v_mfma_f32_16x16x32_bf16 v[30:33], v[164:167], v[216:219], v[30:33]
	v_mfma_f32_16x16x32_bf16 v[22:25], v[168:171], v[212:215], v[22:25]
	v_mfma_f32_16x16x32_bf16 v[22:25], v[172:175], v[216:219], v[22:25]
	v_mfma_f32_16x16x32_bf16 v[26:29], v[176:179], v[212:215], v[26:29]
	v_mfma_f32_16x16x32_bf16 v[26:29], v[184:187], v[216:219], v[26:29]
	v_mfma_f32_16x16x32_bf16 v[18:21], v[188:191], v[212:215], v[18:21]
	v_mfma_f32_16x16x32_bf16 v[18:21], v[192:195], v[216:219], v[18:21]
	v_mfma_f32_16x16x32_bf16 v[14:17], v[148:151], v[220:223], v[14:17]
	v_mfma_f32_16x16x32_bf16 v[14:17], v[164:167], v[224:227], v[14:17]
	v_mfma_f32_16x16x32_bf16 v[6:9], v[168:171], v[220:223], v[6:9]
	v_mfma_f32_16x16x32_bf16 v[6:9], v[172:175], v[224:227], v[6:9]
	v_mfma_f32_16x16x32_bf16 v[10:13], v[176:179], v[220:223], v[10:13]
	v_mfma_f32_16x16x32_bf16 v[10:13], v[184:187], v[224:227], v[10:13]
	v_mfma_f32_16x16x32_bf16 v[2:5], v[188:191], v[220:223], v[2:5]
	v_mfma_f32_16x16x32_bf16 v[2:5], v[192:195], v[224:227], v[2:5]
	s_barrier
	s_add_i32 s83, 0, 0x18000
	s_add_i32 s84, 0, 0x1c000
	ds_read_b128 v[148:151], v246
	ds_read_b128 v[164:167], v246 offset:1024
	ds_read_b128 v[168:171], v246 offset:2048
	ds_read_b128 v[172:175], v246 offset:3072
	ds_read_b128 v[176:179], v247
	ds_read_b128 v[184:187], v247 offset:1024
	ds_read_b128 v[188:191], v247 offset:2048
	ds_read_b128 v[192:195], v247 offset:3072
	s_add_u32 s42, s42, 0x100000
	s_addc_u32 s43, s43, 0
	s_mov_b32 m0, s46
	ds_read_b128 v[196:199], v161 offset:32768
	ds_read_b128 v[200:203], v161 offset:33792
	ds_read_b128 v[204:207], v161 offset:34816
	ds_read_b128 v[208:211], v161 offset:35840
	ds_read_b128 v[212:215], v161 offset:36864
	ds_read_b128 v[216:219], v161 offset:37888
	ds_read_b128 v[220:223], v161 offset:38912
	ds_read_b128 v[224:227], v161 offset:39936
	global_load_lds_dwordx4 v130, s[42:43]
	s_mov_b32 m0, s47
	s_nop 0
	global_load_lds_dwordx4 v134, s[42:43]
	s_waitcnt vmcnt(8)
	s_waitcnt lgkmcnt(0)
	s_barrier
	v_mfma_f32_16x16x32_bf16 v[126:129], v[148:151], v[196:199], v[126:129]
	v_mfma_f32_16x16x32_bf16 v[126:129], v[164:167], v[200:203], v[126:129]
	v_mfma_f32_16x16x32_bf16 v[118:121], v[168:171], v[196:199], v[118:121]
	v_mfma_f32_16x16x32_bf16 v[118:121], v[172:175], v[200:203], v[118:121]
	v_mfma_f32_16x16x32_bf16 v[122:125], v[176:179], v[196:199], v[122:125]
	v_mfma_f32_16x16x32_bf16 v[122:125], v[184:187], v[200:203], v[122:125]
	v_mfma_f32_16x16x32_bf16 v[114:117], v[188:191], v[196:199], v[114:117]
	v_mfma_f32_16x16x32_bf16 v[114:117], v[192:195], v[200:203], v[114:117]
	v_mfma_f32_16x16x32_bf16 v[110:113], v[148:151], v[204:207], v[110:113]
	v_mfma_f32_16x16x32_bf16 v[110:113], v[164:167], v[208:211], v[110:113]
	v_mfma_f32_16x16x32_bf16 v[102:105], v[168:171], v[204:207], v[102:105]
	v_mfma_f32_16x16x32_bf16 v[102:105], v[172:175], v[208:211], v[102:105]
	v_mfma_f32_16x16x32_bf16 v[106:109], v[176:179], v[204:207], v[106:109]
	v_mfma_f32_16x16x32_bf16 v[106:109], v[184:187], v[208:211], v[106:109]
	v_mfma_f32_16x16x32_bf16 v[98:101], v[188:191], v[204:207], v[98:101]
	v_mfma_f32_16x16x32_bf16 v[98:101], v[192:195], v[208:211], v[98:101]
	v_mfma_f32_16x16x32_bf16 v[94:97], v[148:151], v[212:215], v[94:97]
	v_mfma_f32_16x16x32_bf16 v[94:97], v[164:167], v[216:219], v[94:97]
	v_mfma_f32_16x16x32_bf16 v[86:89], v[168:171], v[212:215], v[86:89]
	v_mfma_f32_16x16x32_bf16 v[86:89], v[172:175], v[216:219], v[86:89]
	v_mfma_f32_16x16x32_bf16 v[90:93], v[176:179], v[212:215], v[90:93]
	v_mfma_f32_16x16x32_bf16 v[90:93], v[184:187], v[216:219], v[90:93]
	v_mfma_f32_16x16x32_bf16 v[82:85], v[188:191], v[212:215], v[82:85]
	v_mfma_f32_16x16x32_bf16 v[82:85], v[192:195], v[216:219], v[82:85]
	v_mfma_f32_16x16x32_bf16 v[78:81], v[148:151], v[220:223], v[78:81]
	v_mfma_f32_16x16x32_bf16 v[78:81], v[164:167], v[224:227], v[78:81]
	v_mfma_f32_16x16x32_bf16 v[70:73], v[168:171], v[220:223], v[70:73]
	v_mfma_f32_16x16x32_bf16 v[70:73], v[172:175], v[224:227], v[70:73]
	v_mfma_f32_16x16x32_bf16 v[74:77], v[176:179], v[220:223], v[74:77]
	v_mfma_f32_16x16x32_bf16 v[74:77], v[184:187], v[224:227], v[74:77]
	v_mfma_f32_16x16x32_bf16 v[66:69], v[188:191], v[220:223], v[66:69]
	v_mfma_f32_16x16x32_bf16 v[66:69], v[192:195], v[224:227], v[66:69]
	s_barrier
	s_add_i32 s42, s83, s13
	s_mov_b32 m0, s42
	ds_read_b128 v[196:199], v161 offset:49152
	ds_read_b128 v[200:203], v161 offset:50176
	ds_read_b128 v[204:207], v161 offset:51200
	ds_read_b128 v[208:211], v161 offset:52224
	ds_read_b128 v[212:215], v161 offset:53248
	ds_read_b128 v[216:219], v161 offset:54272
	ds_read_b128 v[220:223], v161 offset:55296
	ds_read_b128 v[224:227], v161 offset:56320
	global_load_lds_dwordx4 v132, s[98:99]
	s_add_i32 m0, s42, 0x2000
	s_add_u32 s40, s40, 0x100080
	s_addc_u32 s41, s41, 0
	s_add_i32 s42, s84, s13
	global_load_lds_dwordx4 v136, s[98:99]
	s_mov_b32 m0, s42
	s_nop 0
	global_load_lds_dwordx4 v132, s[40:41]
	s_add_i32 m0, s42, 0x2000
	s_nop 0
	global_load_lds_dwordx4 v136, s[40:41]
	s_mov_b32 m0, s59
	s_nop 0
	global_load_lds_dwordx4 v130, s[100:101]
	s_mov_b32 m0, s62
	s_nop 0
	global_load_lds_dwordx4 v134, s[100:101]
	s_waitcnt vmcnt(8)
	s_waitcnt lgkmcnt(0)
	s_barrier
	v_mfma_f32_16x16x32_bf16 v[62:65], v[148:151], v[196:199], v[62:65]
	v_mfma_f32_16x16x32_bf16 v[62:65], v[164:167], v[200:203], v[62:65]
	v_mfma_f32_16x16x32_bf16 v[54:57], v[168:171], v[196:199], v[54:57]
	v_mfma_f32_16x16x32_bf16 v[54:57], v[172:175], v[200:203], v[54:57]
	v_mfma_f32_16x16x32_bf16 v[58:61], v[176:179], v[196:199], v[58:61]
	v_mfma_f32_16x16x32_bf16 v[58:61], v[184:187], v[200:203], v[58:61]
	v_mfma_f32_16x16x32_bf16 v[50:53], v[188:191], v[196:199], v[50:53]
	v_mfma_f32_16x16x32_bf16 v[50:53], v[192:195], v[200:203], v[50:53]
	v_mfma_f32_16x16x32_bf16 v[46:49], v[148:151], v[204:207], v[46:49]
	v_mfma_f32_16x16x32_bf16 v[46:49], v[164:167], v[208:211], v[46:49]
	v_mfma_f32_16x16x32_bf16 v[38:41], v[168:171], v[204:207], v[38:41]
	v_mfma_f32_16x16x32_bf16 v[38:41], v[172:175], v[208:211], v[38:41]
	v_mfma_f32_16x16x32_bf16 v[42:45], v[176:179], v[204:207], v[42:45]
	v_mfma_f32_16x16x32_bf16 v[42:45], v[184:187], v[208:211], v[42:45]
	v_mfma_f32_16x16x32_bf16 v[34:37], v[188:191], v[204:207], v[34:37]
	v_mfma_f32_16x16x32_bf16 v[34:37], v[192:195], v[208:211], v[34:37]
	v_mfma_f32_16x16x32_bf16 v[30:33], v[148:151], v[212:215], v[30:33]
	v_mfma_f32_16x16x32_bf16 v[30:33], v[164:167], v[216:219], v[30:33]
	v_mfma_f32_16x16x32_bf16 v[22:25], v[168:171], v[212:215], v[22:25]
	v_mfma_f32_16x16x32_bf16 v[22:25], v[172:175], v[216:219], v[22:25]
	v_mfma_f32_16x16x32_bf16 v[26:29], v[176:179], v[212:215], v[26:29]
	v_mfma_f32_16x16x32_bf16 v[26:29], v[184:187], v[216:219], v[26:29]
	v_mfma_f32_16x16x32_bf16 v[18:21], v[188:191], v[212:215], v[18:21]
	v_mfma_f32_16x16x32_bf16 v[18:21], v[192:195], v[216:219], v[18:21]
	v_mfma_f32_16x16x32_bf16 v[14:17], v[148:151], v[220:223], v[14:17]
	v_mfma_f32_16x16x32_bf16 v[14:17], v[164:167], v[224:227], v[14:17]
	v_mfma_f32_16x16x32_bf16 v[6:9], v[168:171], v[220:223], v[6:9]
	v_mfma_f32_16x16x32_bf16 v[6:9], v[172:175], v[224:227], v[6:9]
	v_mfma_f32_16x16x32_bf16 v[10:13], v[176:179], v[220:223], v[10:13]
	v_mfma_f32_16x16x32_bf16 v[10:13], v[184:187], v[224:227], v[10:13]
	v_mfma_f32_16x16x32_bf16 v[2:5], v[188:191], v[220:223], v[2:5]
	v_mfma_f32_16x16x32_bf16 v[2:5], v[192:195], v[224:227], v[2:5]
	s_barrier
	s_add_i32 s82, s82, 2
	s_add_u32 s6, s6, 0x100
	s_addc_u32 s7, s7, 0
	s_add_u32 s80, s80, 0x100
	s_addc_u32 s81, s81, 0
	s_cmp_gt_u32 s82, 61
	s_cbranch_scc0 .LBB0_2720
	s_and_b64 vcc, exec, s[24:25]
	s_cbranch_vccz .LBB0_2723
	s_barrier

.LBB0_2805:
	ds_read_b128 v[130:133], v163
	ds_read_b128 v[134:137], v163 offset:1024
	ds_read_b128 v[138:141], v163 offset:2048
	ds_read_b128 v[142:145], v163 offset:3072
	ds_read_b128 v[146:149], v188
	ds_read_b128 v[150:153], v188 offset:1024
	ds_read_b128 v[174:177], v188 offset:2048
	ds_read_b128 v[178:181], v188 offset:3072
	s_add_u32 s28, s26, 0xffd50080
	s_addc_u32 s29, s27, -1
	s_cmpk_eq_i32 s62, 0xa8
	s_cselect_b32 s37, s7, s29
	s_cselect_b32 s36, s6, s28
	s_cselect_b32 s29, s25, s59
	s_cselect_b32 s28, s24, s12
	s_add_i32 m0, s38, 0xc000
	ds_read_b128 v[184:187], v189
	ds_read_b128 v[192:195], v189 offset:1024
	ds_read_b128 v[196:199], v189 offset:2048
	ds_read_b128 v[200:203], v189 offset:3072
	ds_read_b128 v[204:207], v189 offset:4096
	ds_read_b128 v[208:211], v189 offset:5120
	ds_read_b128 v[212:215], v189 offset:6144
	ds_read_b128 v[216:219], v189 offset:7168
	global_load_lds_dwordx4 v166, s[26:27]
	s_add_i32 m0, s38, 0xe000
	s_nop 0
	global_load_lds_dwordx4 v168, s[26:27]
	s_waitcnt vmcnt(8)
	s_waitcnt lgkmcnt(0)
	s_barrier
	v_mfma_f32_16x16x32_bf16 v[126:129], v[130:133], v[184:187], v[126:129]
	v_mfma_f32_16x16x32_bf16 v[126:129], v[134:137], v[192:195], v[126:129]
	v_mfma_f32_16x16x32_bf16 v[122:125], v[138:141], v[184:187], v[122:125]
	v_mfma_f32_16x16x32_bf16 v[122:125], v[142:145], v[192:195], v[122:125]
	v_mfma_f32_16x16x32_bf16 v[118:121], v[146:149], v[184:187], v[118:121]
	v_mfma_f32_16x16x32_bf16 v[118:121], v[150:153], v[192:195], v[118:121]
	v_mfma_f32_16x16x32_bf16 v[114:117], v[174:177], v[184:187], v[114:117]
	v_mfma_f32_16x16x32_bf16 v[114:117], v[178:181], v[192:195], v[114:117]
	v_mfma_f32_16x16x32_bf16 v[110:113], v[130:133], v[196:199], v[110:113]
	v_mfma_f32_16x16x32_bf16 v[110:113], v[134:137], v[200:203], v[110:113]
	v_mfma_f32_16x16x32_bf16 v[106:109], v[138:141], v[196:199], v[106:109]
	v_mfma_f32_16x16x32_bf16 v[106:109], v[142:145], v[200:203], v[106:109]
	v_mfma_f32_16x16x32_bf16 v[102:105], v[146:149], v[196:199], v[102:105]
	v_mfma_f32_16x16x32_bf16 v[102:105], v[150:153], v[200:203], v[102:105]
	v_mfma_f32_16x16x32_bf16 v[98:101], v[174:177], v[196:199], v[98:101]
	v_mfma_f32_16x16x32_bf16 v[98:101], v[178:181], v[200:203], v[98:101]
	v_mfma_f32_16x16x32_bf16 v[94:97], v[130:133], v[204:207], v[94:97]
	v_mfma_f32_16x16x32_bf16 v[94:97], v[134:137], v[208:211], v[94:97]
	v_mfma_f32_16x16x32_bf16 v[90:93], v[138:141], v[204:207], v[90:93]
	v_mfma_f32_16x16x32_bf16 v[90:93], v[142:145], v[208:211], v[90:93]
	v_mfma_f32_16x16x32_bf16 v[86:89], v[146:149], v[204:207], v[86:89]
	v_mfma_f32_16x16x32_bf16 v[86:89], v[150:153], v[208:211], v[86:89]
	v_mfma_f32_16x16x32_bf16 v[82:85], v[174:177], v[204:207], v[82:85]
	v_mfma_f32_16x16x32_bf16 v[82:85], v[178:181], v[208:211], v[82:85]
	v_mfma_f32_16x16x32_bf16 v[78:81], v[130:133], v[212:215], v[78:81]
	v_mfma_f32_16x16x32_bf16 v[78:81], v[134:137], v[216:219], v[78:81]
	v_mfma_f32_16x16x32_bf16 v[74:77], v[138:141], v[212:215], v[74:77]
	v_mfma_f32_16x16x32_bf16 v[74:77], v[142:145], v[216:219], v[74:77]
	v_mfma_f32_16x16x32_bf16 v[70:73], v[146:149], v[212:215], v[70:73]
	v_mfma_f32_16x16x32_bf16 v[70:73], v[150:153], v[216:219], v[70:73]
	v_mfma_f32_16x16x32_bf16 v[66:69], v[174:177], v[212:215], v[66:69]
	v_mfma_f32_16x16x32_bf16 v[66:69], v[178:181], v[216:219], v[66:69]
	s_barrier
	s_add_i32 s63, s47, s35
	s_add_u32 s98, s28, 0x80
	s_addc_u32 s99, s29, 0
	s_mov_b32 m0, s63
	ds_read_b128 v[184:187], v189 offset:16384
	ds_read_b128 v[192:195], v189 offset:17408
	ds_read_b128 v[196:199], v189 offset:18432
	ds_read_b128 v[200:203], v189 offset:19456
	ds_read_b128 v[204:207], v189 offset:20480
	ds_read_b128 v[208:211], v189 offset:21504
	ds_read_b128 v[212:215], v189 offset:22528
	ds_read_b128 v[216:219], v189 offset:23552
	global_load_lds_dwordx4 v156, s[28:29]
	s_add_i32 m0, s63, 0x2000
	s_add_u32 s66, s28, 0x2b0000
	s_addc_u32 s67, s29, 0
	s_add_i32 s63, s48, s35
	global_load_lds_dwordx4 v160, s[28:29]
	s_mov_b32 m0, s63
	global_load_lds_dwordx4 v156, s[66:67]
	s_add_i32 m0, s63, 0x2000
	s_nop 0
	global_load_lds_dwordx4 v160, s[66:67]
	s_add_u32 s100, s36, 0x80
	s_addc_u32 s101, s37, 0
	s_mov_b32 m0, s38
	s_nop 0
	global_load_lds_dwordx4 v154, s[36:37]
	s_mov_b32 m0, s39
	s_nop 0
	global_load_lds_dwordx4 v158, s[36:37]
	s_waitcnt vmcnt(8)
	s_waitcnt lgkmcnt(0)
	s_barrier
	v_mfma_f32_16x16x32_bf16 v[62:65], v[130:133], v[184:187], v[62:65]
	v_mfma_f32_16x16x32_bf16 v[62:65], v[134:137], v[192:195], v[62:65]
	v_mfma_f32_16x16x32_bf16 v[58:61], v[138:141], v[184:187], v[58:61]
	v_mfma_f32_16x16x32_bf16 v[58:61], v[142:145], v[192:195], v[58:61]
	v_mfma_f32_16x16x32_bf16 v[54:57], v[146:149], v[184:187], v[54:57]
	v_mfma_f32_16x16x32_bf16 v[54:57], v[150:153], v[192:195], v[54:57]
	v_mfma_f32_16x16x32_bf16 v[50:53], v[174:177], v[184:187], v[50:53]
	v_mfma_f32_16x16x32_bf16 v[50:53], v[178:181], v[192:195], v[50:53]
	v_mfma_f32_16x16x32_bf16 v[46:49], v[130:133], v[196:199], v[46:49]
	v_mfma_f32_16x16x32_bf16 v[46:49], v[134:137], v[200:203], v[46:49]
	v_mfma_f32_16x16x32_bf16 v[42:45], v[138:141], v[196:199], v[42:45]
	v_mfma_f32_16x16x32_bf16 v[42:45], v[142:145], v[200:203], v[42:45]
	v_mfma_f32_16x16x32_bf16 v[38:41], v[146:149], v[196:199], v[38:41]
	v_mfma_f32_16x16x32_bf16 v[38:41], v[150:153], v[200:203], v[38:41]
	v_mfma_f32_16x16x32_bf16 v[34:37], v[174:177], v[196:199], v[34:37]
	v_mfma_f32_16x16x32_bf16 v[34:37], v[178:181], v[200:203], v[34:37]
	v_mfma_f32_16x16x32_bf16 v[30:33], v[130:133], v[204:207], v[30:33]
	v_mfma_f32_16x16x32_bf16 v[30:33], v[134:137], v[208:211], v[30:33]
	v_mfma_f32_16x16x32_bf16 v[26:29], v[138:141], v[204:207], v[26:29]
	v_mfma_f32_16x16x32_bf16 v[26:29], v[142:145], v[208:211], v[26:29]
	v_mfma_f32_16x16x32_bf16 v[22:25], v[146:149], v[204:207], v[22:25]
	v_mfma_f32_16x16x32_bf16 v[22:25], v[150:153], v[208:211], v[22:25]
	v_mfma_f32_16x16x32_bf16 v[18:21], v[174:177], v[204:207], v[18:21]
	v_mfma_f32_16x16x32_bf16 v[18:21], v[178:181], v[208:211], v[18:21]
	v_mfma_f32_16x16x32_bf16 v[14:17], v[130:133], v[212:215], v[14:17]
	v_mfma_f32_16x16x32_bf16 v[14:17], v[134:137], v[216:219], v[14:17]
	v_mfma_f32_16x16x32_bf16 v[10:13], v[138:141], v[212:215], v[10:13]
	v_mfma_f32_16x16x32_bf16 v[10:13], v[142:145], v[216:219], v[10:13]
	v_mfma_f32_16x16x32_bf16 v[6:9], v[146:149], v[212:215], v[6:9]
	v_mfma_f32_16x16x32_bf16 v[6:9], v[150:153], v[216:219], v[6:9]
	v_mfma_f32_16x16x32_bf16 v[2:5], v[174:177], v[212:215], v[2:5]
	v_mfma_f32_16x16x32_bf16 v[2:5], v[178:181], v[216:219], v[2:5]
	s_barrier
	s_add_i32 s63, 0, 0x18000
	s_add_i32 s65, 0, 0x1c000
	ds_read_b128 v[130:133], v246
	ds_read_b128 v[134:137], v246 offset:1024
	ds_read_b128 v[138:141], v246 offset:2048
	ds_read_b128 v[142:145], v246 offset:3072
	ds_read_b128 v[146:149], v247
	ds_read_b128 v[150:153], v247 offset:1024
	ds_read_b128 v[174:177], v247 offset:2048
	ds_read_b128 v[178:181], v247 offset:3072
	s_add_u32 s36, s36, 0x2b0000
	s_addc_u32 s37, s37, 0
	s_mov_b32 m0, s40
	ds_read_b128 v[184:187], v189 offset:32768
	ds_read_b128 v[192:195], v189 offset:33792
	ds_read_b128 v[196:199], v189 offset:34816
	ds_read_b128 v[200:203], v189 offset:35840
	ds_read_b128 v[204:207], v189 offset:36864
	ds_read_b128 v[208:211], v189 offset:37888
	ds_read_b128 v[212:215], v189 offset:38912
	ds_read_b128 v[216:219], v189 offset:39936
	global_load_lds_dwordx4 v154, s[36:37]
	s_mov_b32 m0, s41
	s_nop 0
	global_load_lds_dwordx4 v158, s[36:37]
	s_waitcnt vmcnt(8)
	s_waitcnt lgkmcnt(0)
	s_barrier
	v_mfma_f32_16x16x32_bf16 v[126:129], v[130:133], v[184:187], v[126:129]
	v_mfma_f32_16x16x32_bf16 v[126:129], v[134:137], v[192:195], v[126:129]
	v_mfma_f32_16x16x32_bf16 v[122:125], v[138:141], v[184:187], v[122:125]
	v_mfma_f32_16x16x32_bf16 v[122:125], v[142:145], v[192:195], v[122:125]
	v_mfma_f32_16x16x32_bf16 v[118:121], v[146:149], v[184:187], v[118:121]
	v_mfma_f32_16x16x32_bf16 v[118:121], v[150:153], v[192:195], v[118:121]
	v_mfma_f32_16x16x32_bf16 v[114:117], v[174:177], v[184:187], v[114:117]
	v_mfma_f32_16x16x32_bf16 v[114:117], v[178:181], v[192:195], v[114:117]
	v_mfma_f32_16x16x32_bf16 v[110:113], v[130:133], v[196:199], v[110:113]
	v_mfma_f32_16x16x32_bf16 v[110:113], v[134:137], v[200:203], v[110:113]
	v_mfma_f32_16x16x32_bf16 v[106:109], v[138:141], v[196:199], v[106:109]
	v_mfma_f32_16x16x32_bf16 v[106:109], v[142:145], v[200:203], v[106:109]
	v_mfma_f32_16x16x32_bf16 v[102:105], v[146:149], v[196:199], v[102:105]
	v_mfma_f32_16x16x32_bf16 v[102:105], v[150:153], v[200:203], v[102:105]
	v_mfma_f32_16x16x32_bf16 v[98:101], v[174:177], v[196:199], v[98:101]
	v_mfma_f32_16x16x32_bf16 v[98:101], v[178:181], v[200:203], v[98:101]
	v_mfma_f32_16x16x32_bf16 v[94:97], v[130:133], v[204:207], v[94:97]
	v_mfma_f32_16x16x32_bf16 v[94:97], v[134:137], v[208:211], v[94:97]
	v_mfma_f32_16x16x32_bf16 v[90:93], v[138:141], v[204:207], v[90:93]
	v_mfma_f32_16x16x32_bf16 v[90:93], v[142:145], v[208:211], v[90:93]
	v_mfma_f32_16x16x32_bf16 v[86:89], v[146:149], v[204:207], v[86:89]
	v_mfma_f32_16x16x32_bf16 v[86:89], v[150:153], v[208:211], v[86:89]
	v_mfma_f32_16x16x32_bf16 v[82:85], v[174:177], v[204:207], v[82:85]
	v_mfma_f32_16x16x32_bf16 v[82:85], v[178:181], v[208:211], v[82:85]
	v_mfma_f32_16x16x32_bf16 v[78:81], v[130:133], v[212:215], v[78:81]
	v_mfma_f32_16x16x32_bf16 v[78:81], v[134:137], v[216:219], v[78:81]
	v_mfma_f32_16x16x32_bf16 v[74:77], v[138:141], v[212:215], v[74:77]
	v_mfma_f32_16x16x32_bf16 v[74:77], v[142:145], v[216:219], v[74:77]
	v_mfma_f32_16x16x32_bf16 v[70:73], v[146:149], v[212:215], v[70:73]
	v_mfma_f32_16x16x32_bf16 v[70:73], v[150:153], v[216:219], v[70:73]
	v_mfma_f32_16x16x32_bf16 v[66:69], v[174:177], v[212:215], v[66:69]
	v_mfma_f32_16x16x32_bf16 v[66:69], v[178:181], v[216:219], v[66:69]
	s_barrier
	s_add_i32 s36, s63, s35
	s_mov_b32 m0, s36
	ds_read_b128 v[184:187], v189 offset:49152
	ds_read_b128 v[192:195], v189 offset:50176
	ds_read_b128 v[196:199], v189 offset:51200
	ds_read_b128 v[200:203], v189 offset:52224
	ds_read_b128 v[204:207], v189 offset:53248
	ds_read_b128 v[208:211], v189 offset:54272
	ds_read_b128 v[212:215], v189 offset:55296
	ds_read_b128 v[216:219], v189 offset:56320
	global_load_lds_dwordx4 v156, s[98:99]
	s_add_i32 m0, s36, 0x2000
	s_add_u32 s28, s28, 0x2b0080
	s_addc_u32 s29, s29, 0
	s_add_i32 s36, s65, s35
	global_load_lds_dwordx4 v160, s[98:99]
	s_mov_b32 m0, s36
	s_nop 0
	global_load_lds_dwordx4 v156, s[28:29]
	s_add_i32 m0, s36, 0x2000
	s_nop 0
	global_load_lds_dwordx4 v160, s[28:29]
	s_mov_b32 m0, s43
	s_nop 0
	global_load_lds_dwordx4 v154, s[100:101]
	s_mov_b32 m0, s44
	s_nop 0
	global_load_lds_dwordx4 v158, s[100:101]
	s_waitcnt vmcnt(8)
	s_waitcnt lgkmcnt(0)
	s_barrier
	v_mfma_f32_16x16x32_bf16 v[62:65], v[130:133], v[184:187], v[62:65]
	v_mfma_f32_16x16x32_bf16 v[62:65], v[134:137], v[192:195], v[62:65]
	v_mfma_f32_16x16x32_bf16 v[58:61], v[138:141], v[184:187], v[58:61]
	v_mfma_f32_16x16x32_bf16 v[58:61], v[142:145], v[192:195], v[58:61]
	v_mfma_f32_16x16x32_bf16 v[54:57], v[146:149], v[184:187], v[54:57]
	v_mfma_f32_16x16x32_bf16 v[54:57], v[150:153], v[192:195], v[54:57]
	v_mfma_f32_16x16x32_bf16 v[50:53], v[174:177], v[184:187], v[50:53]
	v_mfma_f32_16x16x32_bf16 v[50:53], v[178:181], v[192:195], v[50:53]
	v_mfma_f32_16x16x32_bf16 v[46:49], v[130:133], v[196:199], v[46:49]
	v_mfma_f32_16x16x32_bf16 v[46:49], v[134:137], v[200:203], v[46:49]
	v_mfma_f32_16x16x32_bf16 v[42:45], v[138:141], v[196:199], v[42:45]
	v_mfma_f32_16x16x32_bf16 v[42:45], v[142:145], v[200:203], v[42:45]
	v_mfma_f32_16x16x32_bf16 v[38:41], v[146:149], v[196:199], v[38:41]
	v_mfma_f32_16x16x32_bf16 v[38:41], v[150:153], v[200:203], v[38:41]
	v_mfma_f32_16x16x32_bf16 v[34:37], v[174:177], v[196:199], v[34:37]
	v_mfma_f32_16x16x32_bf16 v[34:37], v[178:181], v[200:203], v[34:37]
	v_mfma_f32_16x16x32_bf16 v[30:33], v[130:133], v[204:207], v[30:33]
	v_mfma_f32_16x16x32_bf16 v[30:33], v[134:137], v[208:211], v[30:33]
	v_mfma_f32_16x16x32_bf16 v[26:29], v[138:141], v[204:207], v[26:29]
	v_mfma_f32_16x16x32_bf16 v[26:29], v[142:145], v[208:211], v[26:29]
	v_mfma_f32_16x16x32_bf16 v[22:25], v[146:149], v[204:207], v[22:25]
	v_mfma_f32_16x16x32_bf16 v[22:25], v[150:153], v[208:211], v[22:25]
	v_mfma_f32_16x16x32_bf16 v[18:21], v[174:177], v[204:207], v[18:21]
	v_mfma_f32_16x16x32_bf16 v[18:21], v[178:181], v[208:211], v[18:21]
	v_mfma_f32_16x16x32_bf16 v[14:17], v[130:133], v[212:215], v[14:17]
	v_mfma_f32_16x16x32_bf16 v[14:17], v[134:137], v[216:219], v[14:17]
	v_mfma_f32_16x16x32_bf16 v[10:13], v[138:141], v[212:215], v[10:13]
	v_mfma_f32_16x16x32_bf16 v[10:13], v[142:145], v[216:219], v[10:13]
	v_mfma_f32_16x16x32_bf16 v[6:9], v[146:149], v[212:215], v[6:9]
	v_mfma_f32_16x16x32_bf16 v[6:9], v[150:153], v[216:219], v[6:9]
	v_mfma_f32_16x16x32_bf16 v[2:5], v[174:177], v[212:215], v[2:5]
	v_mfma_f32_16x16x32_bf16 v[2:5], v[178:181], v[216:219], v[2:5]
	s_barrier
	s_add_i32 s62, s62, 2
	s_add_u32 s26, s26, 0x100
	s_addc_u32 s27, s27, 0
	s_add_u32 s12, s12, 0x100
	s_addc_u32 s59, s59, 0
	s_cmpk_gt_u32 s62, 0xa9
	s_cbranch_scc0 .LBB0_2805
	s_and_b64 vcc, exec, s[22:23]
	s_cbranch_vccz .LBB0_2808
	s_barrier
